# v12
# speedup vs baseline: 1.0080x; 1.0029x over previous
.LBB0_217:
	v_cndmask_b32_e64 v147, v147, v186, s[0:1]
	v_mul_f32_e32 v147, 0xbe0293ee, v147
	v_fmamk_f32 v80, v80, 0x3e0293ee, v147
	v_fmamk_f32 v81, v81, 0x3e0293ee, v147
	v_fmamk_f32 v148, v82, 0x3e0293ee, v147
	v_exp_f32_e32 v82, v80
	v_fmamk_f32 v149, v84, 0x3e0293ee, v147
	v_exp_f32_e32 v84, v81
	v_fmamk_f32 v83, v83, 0x3e0293ee, v147
	v_exp_f32_e32 v80, v148
	v_fmamk_f32 v64, v64, 0x3e0293ee, v147
	v_exp_f32_e32 v83, v83
	v_fmamk_f32 v150, v85, 0x3e0293ee, v147
	v_fmamk_f32 v159, v94, 0x3e0293ee, v147
	v_fmamk_f32 v94, v75, 0x3e0293ee, v147
	v_exp_f32_e32 v75, v149
	v_exp_f32_e32 v148, v64
	v_add_f32_e32 v64, 0, v82
	v_fmamk_f32 v151, v86, 0x3e0293ee, v147
	v_exp_f32_e32 v81, v150
	v_add_f32_e32 v64, v84, v64
	v_fmamk_f32 v152, v87, 0x3e0293ee, v147
	v_fmamk_f32 v158, v93, 0x3e0293ee, v147
	v_fmamk_f32 v93, v74, 0x3e0293ee, v147
	v_exp_f32_e32 v74, v151
	v_add_f32_e32 v64, v80, v64
	v_fmamk_f32 v153, v88, 0x3e0293ee, v147
	v_fmamk_f32 v160, v95, 0x3e0293ee, v147
	v_fmamk_f32 v95, v76, 0x3e0293ee, v147
	v_exp_f32_e32 v76, v152
	v_add_f32_e32 v64, v83, v64
	v_fmamk_f32 v154, v89, 0x3e0293ee, v147
	v_fmamk_f32 v155, v90, 0x3e0293ee, v147
	v_fmamk_f32 v90, v71, 0x3e0293ee, v147
	v_exp_f32_e32 v71, v153
	v_add_f32_e32 v64, v75, v64
	v_fmamk_f32 v157, v92, 0x3e0293ee, v147
	v_fmamk_f32 v92, v73, 0x3e0293ee, v147
	v_exp_f32_e32 v73, v154
	v_add_f32_e32 v64, v81, v64
	v_fmamk_f32 v156, v91, 0x3e0293ee, v147
	v_fmamk_f32 v88, v69, 0x3e0293ee, v147
	v_exp_f32_e32 v69, v155
	v_add_f32_e32 v64, v74, v64
	v_fmamk_f32 v91, v72, 0x3e0293ee, v147
	v_exp_f32_e32 v72, v156
	v_add_f32_e32 v64, v76, v64
	v_fmamk_f32 v86, v67, 0x3e0293ee, v147
	v_exp_f32_e32 v67, v157
	v_add_f32_e32 v64, v71, v64
	v_fmamk_f32 v89, v70, 0x3e0293ee, v147
	v_exp_f32_e32 v70, v158
	v_add_f32_e32 v64, v73, v64
	v_fmamk_f32 v85, v66, 0x3e0293ee, v147
	v_exp_f32_e32 v66, v159
	v_add_f32_e32 v64, v69, v64
	v_fmamk_f32 v87, v68, 0x3e0293ee, v147
	v_exp_f32_e32 v68, v160
	v_add_f32_e32 v64, v72, v64
	v_fmamk_f32 v65, v65, 0x3e0293ee, v147
	v_add_f32_e32 v64, v67, v64
	v_exp_f32_e32 v149, v65
	v_add_f32_e32 v64, v70, v64
	v_exp_f32_e32 v85, v85
	v_add_f32_e32 v64, v66, v64
	v_exp_f32_e32 v86, v86
	v_add_f32_e32 v64, v68, v64
	v_exp_f32_e32 v87, v87
	v_add_f32_e32 v64, v148, v64
	v_exp_f32_e32 v88, v88
	v_add_f32_e32 v64, v149, v64
	v_exp_f32_e32 v89, v89
	v_add_f32_e32 v64, v85, v64
	v_exp_f32_e32 v90, v90
	v_add_f32_e32 v64, v86, v64
	v_exp_f32_e32 v91, v91
	v_add_f32_e32 v64, v87, v64
	v_exp_f32_e32 v92, v92
	v_add_f32_e32 v64, v88, v64
	v_exp_f32_e32 v93, v93
	v_add_f32_e32 v64, v89, v64
	v_exp_f32_e32 v94, v94
	v_add_f32_e32 v64, v90, v64
	v_fmamk_f32 v77, v77, 0x3e0293ee, v147
	v_exp_f32_e32 v95, v95
	v_add_f32_e32 v64, v91, v64
	v_fmamk_f32 v78, v78, 0x3e0293ee, v147
	v_exp_f32_e32 v150, v77
	v_add_f32_e32 v64, v92, v64
	v_fmac_f32_e32 v147, 0x3e0293ee, v79
	v_exp_f32_e32 v151, v78
	v_add_f32_e32 v64, v93, v64
	v_exp_f32_e32 v147, v147
	v_add_f32_e32 v64, v94, v64
	v_add_f32_e32 v64, v95, v64
	v_add_f32_e32 v64, v150, v64
	v_add_f32_e32 v64, v151, v64
	v_add_f32_e32 v64, v147, v64
	v_mov_b32_e32 v65, v64
	s_nop 1
	v_permlane32_swap_b32_e32 v64, v65
	s_nop 0
	v_cvt_pk_bf16_f32 v78, v82, v84
	s_nop 0
	v_cvt_pk_bf16_f32 v79, v80, v83
	s_nop 0
	v_cvt_pk_bf16_f32 v80, v75, v81
	s_nop 0
	v_cvt_pk_bf16_f32 v81, v74, v76
	s_nop 0
	v_cvt_pk_bf16_f32 v74, v71, v73
	s_nop 0
	v_cvt_pk_bf16_f32 v75, v69, v72
	s_nop 0
	v_cvt_pk_bf16_f32 v76, v67, v70
	s_nop 0
	v_cvt_pk_bf16_f32 v77, v66, v68
	s_nop 0
	v_cvt_pk_bf16_f32 v66, v148, v149
	s_nop 0
	v_cvt_pk_bf16_f32 v67, v85, v86
	s_nop 0
	v_cvt_pk_bf16_f32 v68, v87, v88
	s_nop 0
	v_cvt_pk_bf16_f32 v69, v89, v90
	s_nop 0
	v_cvt_pk_bf16_f32 v70, v91, v92
	s_nop 0
	v_cvt_pk_bf16_f32 v71, v93, v94
	s_nop 0
	v_cvt_pk_bf16_f32 v72, v95, v150
	s_nop 0
	v_cvt_pk_bf16_f32 v73, v151, v147
	s_nop 0
	v_permlane32_swap_b32_e32 v78, v80
	v_permlane32_swap_b32_e32 v79, v81
	v_permlane32_swap_b32_e32 v74, v76
	v_permlane32_swap_b32_e32 v75, v77
	v_permlane32_swap_b32_e32 v66, v68
	v_permlane32_swap_b32_e32 v67, v69
	v_permlane32_swap_b32_e32 v70, v72
	v_permlane32_swap_b32_e32 v71, v73
	ds_read_b64_tr_b16 v[82:83], v173 offset:0x4000
	ds_read_b64_tr_b16 v[84:85], v173 offset:0x4800
	ds_read_b64_tr_b16 v[86:87], v173 offset:0x5000
	ds_read_b64_tr_b16 v[88:89], v173 offset:0x5800
	ds_read_b64_tr_b16 v[90:91], v173 offset:0x6000
	ds_read_b64_tr_b16 v[92:93], v173 offset:0x6800
	ds_read_b64_tr_b16 v[148:149], v173 offset:0x7000
	ds_read_b64_tr_b16 v[150:151], v173 offset:0x7800
	s_waitcnt lgkmcnt(0)
	s_nop 0
	v_mfma_f32_32x32x16_bf16 v[48:63], v[78:81], v[82:85], v[48:63]
	ds_read_b64_tr_b16 v[82:83], v173 offset:0x4200
	ds_read_b64_tr_b16 v[84:85], v173 offset:0x4a00
	v_mfma_f32_32x32x16_bf16 v[48:63], v[74:77], v[86:89], v[48:63]
	ds_read_b64_tr_b16 v[86:87], v173 offset:0x5200
	ds_read_b64_tr_b16 v[88:89], v173 offset:0x5a00
	v_mfma_f32_32x32x16_bf16 v[48:63], v[66:69], v[90:93], v[48:63]
	ds_read_b64_tr_b16 v[90:91], v173 offset:0x6200
	ds_read_b64_tr_b16 v[92:93], v173 offset:0x6a00
	v_mfma_f32_32x32x16_bf16 v[48:63], v[70:73], v[148:151], v[48:63]
	ds_read_b64_tr_b16 v[148:149], v173 offset:0x7200
	ds_read_b64_tr_b16 v[150:151], v173 offset:0x7a00
	s_waitcnt lgkmcnt(0)
	v_mfma_f32_32x32x16_bf16 v[32:47], v[78:81], v[82:85], v[32:47]
	ds_read_b64_tr_b16 v[82:83], v173 offset:0x4400
	ds_read_b64_tr_b16 v[84:85], v173 offset:0x4c00
	v_mfma_f32_32x32x16_bf16 v[32:47], v[74:77], v[86:89], v[32:47]
	ds_read_b64_tr_b16 v[86:87], v173 offset:0x5400
	ds_read_b64_tr_b16 v[88:89], v173 offset:0x5c00
	v_mfma_f32_32x32x16_bf16 v[32:47], v[66:69], v[90:93], v[32:47]
	ds_read_b64_tr_b16 v[90:91], v173 offset:0x6400
	ds_read_b64_tr_b16 v[92:93], v173 offset:0x6c00
	v_mfma_f32_32x32x16_bf16 v[32:47], v[70:73], v[148:151], v[32:47]
	ds_read_b64_tr_b16 v[148:149], v173 offset:0x7400
	ds_read_b64_tr_b16 v[150:151], v173 offset:0x7c00
	s_waitcnt lgkmcnt(0)
	v_mfma_f32_32x32x16_bf16 v[16:31], v[78:81], v[82:85], v[16:31]
	ds_read_b64_tr_b16 v[82:83], v173 offset:0x4600
	ds_read_b64_tr_b16 v[84:85], v173 offset:0x4e00
	v_mfma_f32_32x32x16_bf16 v[16:31], v[74:77], v[86:89], v[16:31]
	ds_read_b64_tr_b16 v[86:87], v173 offset:0x5600
	ds_read_b64_tr_b16 v[88:89], v173 offset:0x5e00
	v_mfma_f32_32x32x16_bf16 v[16:31], v[66:69], v[90:93], v[16:31]
	ds_read_b64_tr_b16 v[90:91], v173 offset:0x6600
	ds_read_b64_tr_b16 v[92:93], v173 offset:0x6e00
	v_mfma_f32_32x32x16_bf16 v[16:31], v[70:73], v[148:151], v[16:31]
	ds_read_b64_tr_b16 v[148:149], v173 offset:0x7600
	ds_read_b64_tr_b16 v[150:151], v173 offset:0x7e00
	s_waitcnt lgkmcnt(0)
	v_mfma_f32_32x32x16_bf16 v[0:15], v[78:81], v[82:85], v[0:15]
	v_mfma_f32_32x32x16_bf16 v[0:15], v[74:77], v[86:89], v[0:15]
	v_mfma_f32_32x32x16_bf16 v[0:15], v[66:69], v[90:93], v[0:15]
	v_mfma_f32_32x32x16_bf16 v[0:15], v[70:73], v[148:151], v[0:15]
	s_waitcnt vmcnt(8)
	s_waitcnt vmcnt(9)
	ds_write_b128 v176, v[136:139] offset:32768
	s_waitcnt vmcnt(8)
	ds_write_b128 v176, v[140:143] offset:40960
	s_and_saveexec_b64 s[0:1], s[4:5]
	v_add_f32_e32 v66, v144, v145
	v_fmac_f32_e32 v66, v177, v192
	v_add_f32_e32 v64, v64, v65
	v_fmac_f32_e32 v64, v66, v146
	ds_write_b32 v175, v64
	s_or_b64 exec, exec, s[0:1]
	s_waitcnt lgkmcnt(0)
	ds_read_b128 v[76:79], v174
	ds_read_b128 v[72:75], v174 offset:32
	v_and_b32_e32 v80, 64, v204
	v_add_u32_e32 v80, 64, v80
	s_ashr_i32 s19, s18, 31
	s_waitcnt lgkmcnt(1)
	v_rcp_f32_e32 v82, v76
	v_xor_b32_e32 v76, 1, v204
	v_cmp_lt_i32_e32 vcc, v76, v80
	ds_read_b128 v[68:71], v174 offset:64
	ds_read_b128 v[64:67], v174 offset:96
	v_cndmask_b32_e32 v76, v204, v76, vcc
	v_lshlrev_b32_e32 v76, 2, v76
	v_mul_f32_e32 v48, v48, v82
	s_lshl_b64 s[0:1], s[18:19], 8
	s_nop 1
	v_mov_b32_dpp v83, v48 quad_perm:[1,0,3,2] row_mask:0xf bank_mask:0xf
	s_add_u32 s0, s16, s0
	s_addc_u32 s1, s17, s1
	v_and_b32_e32 v80, 1, v171
	v_lshlrev_b32_e32 v184, 1, v172
	v_cmp_eq_u32_e64 s[4:5], 0, v80
	v_lshl_add_u64 v[80:81], s[0:1], 0, v[184:185]
	v_lshlrev_b32_e32 v184, 10, v170
	v_lshl_add_u64 v[80:81], v[80:81], 0, v[184:185]
	s_and_saveexec_b64 s[0:1], s[4:5]
	s_cbranch_execz .LBB0_221
	s_waitcnt lgkmcnt(0)
	s_nop 0
	v_cvt_pk_bf16_f32 v48, v48, v83
	global_store_dword v[80:81], v48, off
.LBB0_221:
	s_or_b64 exec, exec, s[0:1]
	v_mul_f32_e32 v32, v32, v82
	s_nop 1
	v_mov_b32_dpp v48, v32 quad_perm:[1,0,3,2] row_mask:0xf bank_mask:0xf
	s_and_saveexec_b64 s[0:1], s[4:5]
	s_cbranch_execz .LBB0_223
	s_waitcnt lgkmcnt(0)
	s_nop 0
	v_cvt_pk_bf16_f32 v32, v32, v48
	global_store_dword v[80:81], v32, off offset:64
.LBB0_223:
	s_or_b64 exec, exec, s[0:1]
	v_mul_f32_e32 v16, v16, v82
	s_nop 1
	v_mov_b32_dpp v32, v16 quad_perm:[1,0,3,2] row_mask:0xf bank_mask:0xf
	s_and_saveexec_b64 s[0:1], s[4:5]
	s_cbranch_execz .LBB0_225
	s_waitcnt lgkmcnt(0)
	s_nop 0
	v_cvt_pk_bf16_f32 v16, v16, v32
	global_store_dword v[80:81], v16, off offset:128
.LBB0_225:
	s_or_b64 exec, exec, s[0:1]
	v_mul_f32_e32 v0, v0, v82
	s_nop 1
	v_mov_b32_dpp v16, v0 quad_perm:[1,0,3,2] row_mask:0xf bank_mask:0xf
	s_and_saveexec_b64 s[0:1], s[4:5]
	s_cbranch_execz .LBB0_227
	s_waitcnt lgkmcnt(0)
	s_nop 0
	v_cvt_pk_bf16_f32 v0, v0, v16
	global_store_dword v[80:81], v0, off offset:192
.LBB0_227:
	s_or_b64 exec, exec, s[0:1]
	v_rcp_f32_e32 v0, v77
	s_waitcnt lgkmcnt(0)
	v_mul_f32_e32 v16, v49, v0
	s_nop 1
	v_mov_b32_dpp v32, v16 quad_perm:[1,0,3,2] row_mask:0xf bank_mask:0xf
	s_and_saveexec_b64 s[0:1], s[4:5]
	s_cbranch_execz .LBB0_229
	s_waitcnt lgkmcnt(0)
	s_nop 0
	v_cvt_pk_bf16_f32 v16, v16, v32
	global_store_dword v[80:81], v16, off offset:256
.LBB0_229:
	s_or_b64 exec, exec, s[0:1]
	v_mul_f32_e32 v16, v33, v0
	s_waitcnt lgkmcnt(0)
	s_nop 1
	v_mov_b32_dpp v32, v16 quad_perm:[1,0,3,2] row_mask:0xf bank_mask:0xf
	s_and_saveexec_b64 s[0:1], s[4:5]
	s_cbranch_execz .LBB0_231
	s_waitcnt lgkmcnt(0)
	s_nop 0
	v_cvt_pk_bf16_f32 v16, v16, v32
	global_store_dword v[80:81], v16, off offset:320
.LBB0_231:
	s_or_b64 exec, exec, s[0:1]
	v_mul_f32_e32 v16, v17, v0
	s_nop 1
	v_mov_b32_dpp v17, v16 quad_perm:[1,0,3,2] row_mask:0xf bank_mask:0xf
	s_and_saveexec_b64 s[0:1], s[4:5]
	s_cbranch_execz .LBB0_233
	s_waitcnt lgkmcnt(0)
	s_nop 0
	v_cvt_pk_bf16_f32 v16, v16, v17
	global_store_dword v[80:81], v16, off offset:384
.LBB0_233:
	s_or_b64 exec, exec, s[0:1]
	v_mul_f32_e32 v0, v1, v0
	s_nop 1
	v_mov_b32_dpp v1, v0 quad_perm:[1,0,3,2] row_mask:0xf bank_mask:0xf
	s_and_saveexec_b64 s[0:1], s[4:5]
	s_cbranch_execz .LBB0_235
	s_waitcnt lgkmcnt(0)
	s_nop 0
	v_cvt_pk_bf16_f32 v0, v0, v1
	global_store_dword v[80:81], v0, off offset:448
.LBB0_235:
	s_or_b64 exec, exec, s[0:1]
	v_rcp_f32_e32 v0, v78
	s_waitcnt lgkmcnt(0)
	v_mul_f32_e32 v1, v50, v0
	s_nop 1
	v_mov_b32_dpp v16, v1 quad_perm:[1,0,3,2] row_mask:0xf bank_mask:0xf
	s_and_saveexec_b64 s[0:1], s[4:5]
	s_cbranch_execz .LBB0_237
	s_waitcnt lgkmcnt(0)
	s_nop 0
	v_cvt_pk_bf16_f32 v1, v1, v16
	global_store_dword v[80:81], v1, off offset:512
.LBB0_237:
	s_or_b64 exec, exec, s[0:1]
	v_mul_f32_e32 v1, v34, v0
	s_waitcnt lgkmcnt(0)
	s_nop 1
	v_mov_b32_dpp v16, v1 quad_perm:[1,0,3,2] row_mask:0xf bank_mask:0xf
	s_and_saveexec_b64 s[0:1], s[4:5]
	s_cbranch_execz .LBB0_239
	s_waitcnt lgkmcnt(0)
	s_nop 0
	v_cvt_pk_bf16_f32 v1, v1, v16
	global_store_dword v[80:81], v1, off offset:576
.LBB0_239:
	s_or_b64 exec, exec, s[0:1]
	v_mul_f32_e32 v1, v18, v0
	s_waitcnt lgkmcnt(0)
	s_nop 1
	v_mov_b32_dpp v16, v1 quad_perm:[1,0,3,2] row_mask:0xf bank_mask:0xf
	s_and_saveexec_b64 s[0:1], s[4:5]
	s_cbranch_execz .LBB0_241
	s_waitcnt lgkmcnt(0)
	s_nop 0
	v_cvt_pk_bf16_f32 v1, v1, v16
	global_store_dword v[80:81], v1, off offset:640
.LBB0_241:
	s_or_b64 exec, exec, s[0:1]
	v_mul_f32_e32 v0, v2, v0
	s_nop 1
	v_mov_b32_dpp v1, v0 quad_perm:[1,0,3,2] row_mask:0xf bank_mask:0xf
	s_and_saveexec_b64 s[0:1], s[4:5]
	s_cbranch_execz .LBB0_243
	s_waitcnt lgkmcnt(0)
	s_nop 0
	v_cvt_pk_bf16_f32 v0, v0, v1
	global_store_dword v[80:81], v0, off offset:704
.LBB0_243:
	s_or_b64 exec, exec, s[0:1]
	v_rcp_f32_e32 v0, v79
	s_waitcnt lgkmcnt(0)
	v_mul_f32_e32 v1, v51, v0
	s_nop 1
	v_mov_b32_dpp v2, v1 quad_perm:[1,0,3,2] row_mask:0xf bank_mask:0xf
	s_and_saveexec_b64 s[0:1], s[4:5]
	s_cbranch_execz .LBB0_245
	s_waitcnt lgkmcnt(0)
	s_nop 0
	v_cvt_pk_bf16_f32 v1, v1, v2
	global_store_dword v[80:81], v1, off offset:768
.LBB0_245:
	s_or_b64 exec, exec, s[0:1]
	v_mul_f32_e32 v1, v35, v0
	s_waitcnt lgkmcnt(0)
	s_nop 1
	v_mov_b32_dpp v2, v1 quad_perm:[1,0,3,2] row_mask:0xf bank_mask:0xf
	s_and_saveexec_b64 s[0:1], s[4:5]
	s_cbranch_execz .LBB0_247
	s_waitcnt lgkmcnt(0)
	s_nop 0
	v_cvt_pk_bf16_f32 v1, v1, v2
	global_store_dword v[80:81], v1, off offset:832
.LBB0_247:
	s_or_b64 exec, exec, s[0:1]
	v_mul_f32_e32 v1, v19, v0
	s_waitcnt lgkmcnt(0)
	s_nop 1
	v_mov_b32_dpp v2, v1 quad_perm:[1,0,3,2] row_mask:0xf bank_mask:0xf
	s_and_saveexec_b64 s[0:1], s[4:5]
	s_cbranch_execz .LBB0_249
	s_waitcnt lgkmcnt(0)
	s_nop 0
	v_cvt_pk_bf16_f32 v1, v1, v2
	global_store_dword v[80:81], v1, off offset:896
.LBB0_249:
	s_or_b64 exec, exec, s[0:1]
	v_mul_f32_e32 v0, v3, v0
	s_nop 1
	v_mov_b32_dpp v1, v0 quad_perm:[1,0,3,2] row_mask:0xf bank_mask:0xf
	s_and_saveexec_b64 s[0:1], s[4:5]
	s_cbranch_execz .LBB0_251
	s_waitcnt lgkmcnt(0)
	s_nop 0
	v_cvt_pk_bf16_f32 v0, v0, v1
	global_store_dword v[80:81], v0, off offset:960
.LBB0_251:
	s_or_b64 exec, exec, s[0:1]
	v_rcp_f32_e32 v0, v72
	s_waitcnt lgkmcnt(0)
	v_mul_f32_e32 v1, v52, v0
	s_nop 1
	v_mov_b32_dpp v2, v1 quad_perm:[1,0,3,2] row_mask:0xf bank_mask:0xf
	s_and_saveexec_b64 s[0:1], s[4:5]
	s_cbranch_execz .LBB0_253
	s_waitcnt lgkmcnt(0)
	s_nop 0
	v_cvt_pk_bf16_f32 v1, v1, v2
	global_store_dword v[80:81], v1, off offset:2048
.LBB0_253:
	s_or_b64 exec, exec, s[0:1]
	v_mul_f32_e32 v1, v36, v0
	s_waitcnt lgkmcnt(0)
	s_nop 1
	v_mov_b32_dpp v2, v1 quad_perm:[1,0,3,2] row_mask:0xf bank_mask:0xf
	s_and_saveexec_b64 s[0:1], s[4:5]
	s_cbranch_execz .LBB0_255
	s_waitcnt lgkmcnt(0)
	s_nop 0
	v_cvt_pk_bf16_f32 v1, v1, v2
	global_store_dword v[80:81], v1, off offset:2112
.LBB0_255:
	s_or_b64 exec, exec, s[0:1]
	v_mul_f32_e32 v1, v20, v0
	s_waitcnt lgkmcnt(0)
	s_nop 1
	v_mov_b32_dpp v2, v1 quad_perm:[1,0,3,2] row_mask:0xf bank_mask:0xf
	s_and_saveexec_b64 s[0:1], s[4:5]
	s_cbranch_execz .LBB0_257
	s_waitcnt lgkmcnt(0)
	s_nop 0
	v_cvt_pk_bf16_f32 v1, v1, v2
	global_store_dword v[80:81], v1, off offset:2176
.LBB0_257:
	s_or_b64 exec, exec, s[0:1]
	v_mul_f32_e32 v0, v4, v0
	s_nop 1
	v_mov_b32_dpp v1, v0 quad_perm:[1,0,3,2] row_mask:0xf bank_mask:0xf
	s_and_saveexec_b64 s[0:1], s[4:5]
	s_cbranch_execz .LBB0_259
	s_waitcnt lgkmcnt(0)
	s_nop 0
	v_cvt_pk_bf16_f32 v0, v0, v1
	global_store_dword v[80:81], v0, off offset:2240
.LBB0_259:
	s_or_b64 exec, exec, s[0:1]
	v_rcp_f32_e32 v0, v73
	s_waitcnt lgkmcnt(0)
	v_mul_f32_e32 v1, v53, v0
	s_nop 1
	v_mov_b32_dpp v2, v1 quad_perm:[1,0,3,2] row_mask:0xf bank_mask:0xf
	s_and_saveexec_b64 s[0:1], s[4:5]
	s_cbranch_execz .LBB0_261
	s_waitcnt lgkmcnt(0)
	s_nop 0
	v_cvt_pk_bf16_f32 v1, v1, v2
	global_store_dword v[80:81], v1, off offset:2304
.LBB0_261:
	s_or_b64 exec, exec, s[0:1]
	v_mul_f32_e32 v1, v37, v0
	s_waitcnt lgkmcnt(0)
	s_nop 1
	v_mov_b32_dpp v2, v1 quad_perm:[1,0,3,2] row_mask:0xf bank_mask:0xf
	s_and_saveexec_b64 s[0:1], s[4:5]
	s_cbranch_execz .LBB0_263
	s_waitcnt lgkmcnt(0)
	s_nop 0
	v_cvt_pk_bf16_f32 v1, v1, v2
	global_store_dword v[80:81], v1, off offset:2368
.LBB0_263:
	s_or_b64 exec, exec, s[0:1]
	v_mul_f32_e32 v1, v21, v0
	s_waitcnt lgkmcnt(0)
	s_nop 1
	v_mov_b32_dpp v2, v1 quad_perm:[1,0,3,2] row_mask:0xf bank_mask:0xf
	s_and_saveexec_b64 s[0:1], s[4:5]
	s_cbranch_execz .LBB0_265
	s_waitcnt lgkmcnt(0)
	s_nop 0
	v_cvt_pk_bf16_f32 v1, v1, v2
	global_store_dword v[80:81], v1, off offset:2432
.LBB0_265:
	s_or_b64 exec, exec, s[0:1]
	v_mul_f32_e32 v0, v5, v0
	s_nop 1
	v_mov_b32_dpp v1, v0 quad_perm:[1,0,3,2] row_mask:0xf bank_mask:0xf
	s_and_saveexec_b64 s[0:1], s[4:5]
	s_cbranch_execz .LBB0_267
	s_waitcnt lgkmcnt(0)
	s_nop 0
	v_cvt_pk_bf16_f32 v0, v0, v1
	global_store_dword v[80:81], v0, off offset:2496
.LBB0_267:
	s_or_b64 exec, exec, s[0:1]
	v_rcp_f32_e32 v0, v74
	s_waitcnt lgkmcnt(0)
	v_mul_f32_e32 v1, v54, v0
	s_nop 1
	v_mov_b32_dpp v2, v1 quad_perm:[1,0,3,2] row_mask:0xf bank_mask:0xf
	s_and_saveexec_b64 s[0:1], s[4:5]
	s_cbranch_execz .LBB0_269
	s_waitcnt lgkmcnt(0)
	s_nop 0
	v_cvt_pk_bf16_f32 v1, v1, v2
	global_store_dword v[80:81], v1, off offset:2560
.LBB0_269:
	s_or_b64 exec, exec, s[0:1]
	v_mul_f32_e32 v1, v38, v0
	s_waitcnt lgkmcnt(0)
	s_nop 1
	v_mov_b32_dpp v2, v1 quad_perm:[1,0,3,2] row_mask:0xf bank_mask:0xf
	s_and_saveexec_b64 s[0:1], s[4:5]
	s_cbranch_execz .LBB0_271
	s_waitcnt lgkmcnt(0)
	s_nop 0
	v_cvt_pk_bf16_f32 v1, v1, v2
	global_store_dword v[80:81], v1, off offset:2624
.LBB0_271:
	s_or_b64 exec, exec, s[0:1]
	v_mul_f32_e32 v1, v22, v0
	s_waitcnt lgkmcnt(0)
	s_nop 1
	v_mov_b32_dpp v2, v1 quad_perm:[1,0,3,2] row_mask:0xf bank_mask:0xf
	s_and_saveexec_b64 s[0:1], s[4:5]
	s_cbranch_execz .LBB0_273
	s_waitcnt lgkmcnt(0)
	s_nop 0
	v_cvt_pk_bf16_f32 v1, v1, v2
	global_store_dword v[80:81], v1, off offset:2688
.LBB0_273:
	s_or_b64 exec, exec, s[0:1]
	v_mul_f32_e32 v0, v6, v0
	s_nop 1
	v_mov_b32_dpp v1, v0 quad_perm:[1,0,3,2] row_mask:0xf bank_mask:0xf
	s_and_saveexec_b64 s[0:1], s[4:5]
	s_cbranch_execz .LBB0_275
	s_waitcnt lgkmcnt(0)
	s_nop 0
	v_cvt_pk_bf16_f32 v0, v0, v1
	global_store_dword v[80:81], v0, off offset:2752
.LBB0_275:
	s_or_b64 exec, exec, s[0:1]
	v_rcp_f32_e32 v0, v75
	s_waitcnt lgkmcnt(0)
	v_mul_f32_e32 v1, v55, v0
	s_nop 1
	v_mov_b32_dpp v2, v1 quad_perm:[1,0,3,2] row_mask:0xf bank_mask:0xf
	s_and_saveexec_b64 s[0:1], s[4:5]
	s_cbranch_execz .LBB0_277
	s_waitcnt lgkmcnt(0)
	s_nop 0
	v_cvt_pk_bf16_f32 v1, v1, v2
	global_store_dword v[80:81], v1, off offset:2816
.LBB0_277:
	s_or_b64 exec, exec, s[0:1]
	v_mul_f32_e32 v1, v39, v0
	s_waitcnt lgkmcnt(0)
	s_nop 1
	v_mov_b32_dpp v2, v1 quad_perm:[1,0,3,2] row_mask:0xf bank_mask:0xf
	s_and_saveexec_b64 s[0:1], s[4:5]
	s_cbranch_execz .LBB0_279
	s_waitcnt lgkmcnt(0)
	s_nop 0
	v_cvt_pk_bf16_f32 v1, v1, v2
	global_store_dword v[80:81], v1, off offset:2880
.LBB0_279:
	s_or_b64 exec, exec, s[0:1]
	v_mul_f32_e32 v1, v23, v0
	s_waitcnt lgkmcnt(0)
	s_nop 1
	v_mov_b32_dpp v2, v1 quad_perm:[1,0,3,2] row_mask:0xf bank_mask:0xf
	s_and_saveexec_b64 s[0:1], s[4:5]
	s_cbranch_execz .LBB0_281
	s_waitcnt lgkmcnt(0)
	s_nop 0
	v_cvt_pk_bf16_f32 v1, v1, v2
	global_store_dword v[80:81], v1, off offset:2944
.LBB0_281:
	s_or_b64 exec, exec, s[0:1]
	v_mul_f32_e32 v0, v7, v0
	s_nop 1
	v_mov_b32_dpp v1, v0 quad_perm:[1,0,3,2] row_mask:0xf bank_mask:0xf
	s_and_saveexec_b64 s[0:1], s[4:5]
	s_cbranch_execz .LBB0_283
	s_waitcnt lgkmcnt(0)
	s_nop 0
	v_cvt_pk_bf16_f32 v0, v0, v1
	global_store_dword v[80:81], v0, off offset:3008
.LBB0_283:
	s_or_b64 exec, exec, s[0:1]
	v_rcp_f32_e32 v0, v68
	s_waitcnt lgkmcnt(0)
	v_mul_f32_e32 v1, v56, v0
	s_nop 1
	v_mov_b32_dpp v2, v1 quad_perm:[1,0,3,2] row_mask:0xf bank_mask:0xf
	s_and_saveexec_b64 s[0:1], s[4:5]
	s_cbranch_execz .LBB0_285
	s_waitcnt lgkmcnt(0)
	s_nop 0
	v_cvt_pk_bf16_f32 v1, v1, v2
	v_add_co_u32_e32 v2, vcc, 0x1000, v80
	s_nop 1
	v_addc_co_u32_e32 v3, vcc, 0, v81, vcc
	global_store_dword v[2:3], v1, off
.LBB0_285:
	s_or_b64 exec, exec, s[0:1]
	v_mul_f32_e32 v1, v40, v0
	s_waitcnt lgkmcnt(0)
	s_nop 1
	v_mov_b32_dpp v2, v1 quad_perm:[1,0,3,2] row_mask:0xf bank_mask:0xf
	s_and_saveexec_b64 s[0:1], s[4:5]
	s_cbranch_execz .LBB0_287
	s_waitcnt lgkmcnt(0)
	s_nop 0
	v_cvt_pk_bf16_f32 v1, v1, v2
	v_add_co_u32_e32 v2, vcc, 0x1000, v80
	s_nop 1
	v_addc_co_u32_e32 v3, vcc, 0, v81, vcc
	global_store_dword v[2:3], v1, off offset:64
.LBB0_287:
	s_or_b64 exec, exec, s[0:1]
	v_mul_f32_e32 v1, v24, v0
	s_waitcnt lgkmcnt(0)
	s_nop 1
	v_mov_b32_dpp v2, v1 quad_perm:[1,0,3,2] row_mask:0xf bank_mask:0xf
	s_and_saveexec_b64 s[0:1], s[4:5]
	s_cbranch_execz .LBB0_289
	s_waitcnt lgkmcnt(0)
	s_nop 0
	v_cvt_pk_bf16_f32 v1, v1, v2
	v_add_co_u32_e32 v2, vcc, 0x1000, v80
	s_nop 1
	v_addc_co_u32_e32 v3, vcc, 0, v81, vcc
	global_store_dword v[2:3], v1, off offset:128
.LBB0_289:
	s_or_b64 exec, exec, s[0:1]
	v_mul_f32_e32 v0, v8, v0
	s_nop 1
	v_mov_b32_dpp v1, v0 quad_perm:[1,0,3,2] row_mask:0xf bank_mask:0xf
	s_and_saveexec_b64 s[0:1], s[4:5]
	s_cbranch_execz .LBB0_291
	s_waitcnt lgkmcnt(0)
	s_nop 0
	v_cvt_pk_bf16_f32 v2, v0, v1
	v_add_co_u32_e32 v0, vcc, 0x1000, v80
	s_nop 1
	v_addc_co_u32_e32 v1, vcc, 0, v81, vcc
	global_store_dword v[0:1], v2, off offset:192
.LBB0_291:
	s_or_b64 exec, exec, s[0:1]
	v_rcp_f32_e32 v0, v69
	s_waitcnt lgkmcnt(0)
	v_mul_f32_e32 v1, v57, v0
	s_nop 1
	v_mov_b32_dpp v2, v1 quad_perm:[1,0,3,2] row_mask:0xf bank_mask:0xf
	s_and_saveexec_b64 s[0:1], s[4:5]
	s_cbranch_execz .LBB0_293
	s_waitcnt lgkmcnt(0)
	s_nop 0
	v_cvt_pk_bf16_f32 v1, v1, v2
	v_add_co_u32_e32 v2, vcc, 0x1000, v80
	s_nop 1
	v_addc_co_u32_e32 v3, vcc, 0, v81, vcc
	global_store_dword v[2:3], v1, off offset:256
.LBB0_293:
	s_or_b64 exec, exec, s[0:1]
	v_mul_f32_e32 v1, v41, v0
	s_waitcnt lgkmcnt(0)
	s_nop 1
	v_mov_b32_dpp v2, v1 quad_perm:[1,0,3,2] row_mask:0xf bank_mask:0xf
	s_and_saveexec_b64 s[0:1], s[4:5]
	s_cbranch_execz .LBB0_295
	s_waitcnt lgkmcnt(0)
	s_nop 0
	v_cvt_pk_bf16_f32 v1, v1, v2
	v_add_co_u32_e32 v2, vcc, 0x1000, v80
	s_nop 1
	v_addc_co_u32_e32 v3, vcc, 0, v81, vcc
	global_store_dword v[2:3], v1, off offset:320
.LBB0_295:
	s_or_b64 exec, exec, s[0:1]
	v_mul_f32_e32 v1, v25, v0
	s_waitcnt lgkmcnt(0)
	s_nop 1
	v_mov_b32_dpp v2, v1 quad_perm:[1,0,3,2] row_mask:0xf bank_mask:0xf
	s_and_saveexec_b64 s[0:1], s[4:5]
	s_cbranch_execz .LBB0_297
	s_waitcnt lgkmcnt(0)
	s_nop 0
	v_cvt_pk_bf16_f32 v1, v1, v2
	v_add_co_u32_e32 v2, vcc, 0x1000, v80
	s_nop 1
	v_addc_co_u32_e32 v3, vcc, 0, v81, vcc
	global_store_dword v[2:3], v1, off offset:384
.LBB0_297:
	s_or_b64 exec, exec, s[0:1]
	v_mul_f32_e32 v0, v9, v0
	s_nop 1
	v_mov_b32_dpp v1, v0 quad_perm:[1,0,3,2] row_mask:0xf bank_mask:0xf
	s_and_saveexec_b64 s[0:1], s[4:5]
	s_cbranch_execz .LBB0_299
	s_waitcnt lgkmcnt(0)
	s_nop 0
	v_cvt_pk_bf16_f32 v2, v0, v1
	v_add_co_u32_e32 v0, vcc, 0x1000, v80
	s_nop 1
	v_addc_co_u32_e32 v1, vcc, 0, v81, vcc
	global_store_dword v[0:1], v2, off offset:448
.LBB0_299:
	s_or_b64 exec, exec, s[0:1]
	v_rcp_f32_e32 v0, v70
	s_waitcnt lgkmcnt(0)
	v_mul_f32_e32 v1, v58, v0
	s_nop 1
	v_mov_b32_dpp v2, v1 quad_perm:[1,0,3,2] row_mask:0xf bank_mask:0xf
	s_and_saveexec_b64 s[0:1], s[4:5]
	s_cbranch_execz .LBB0_301
	s_waitcnt lgkmcnt(0)
	s_nop 0
	v_cvt_pk_bf16_f32 v1, v1, v2
	v_add_co_u32_e32 v2, vcc, 0x1000, v80
	s_nop 1
	v_addc_co_u32_e32 v3, vcc, 0, v81, vcc
	global_store_dword v[2:3], v1, off offset:512
.LBB0_301:
	s_or_b64 exec, exec, s[0:1]
	v_mul_f32_e32 v1, v42, v0
	s_waitcnt lgkmcnt(0)
	s_nop 1
	v_mov_b32_dpp v2, v1 quad_perm:[1,0,3,2] row_mask:0xf bank_mask:0xf
	s_and_saveexec_b64 s[0:1], s[4:5]
	s_cbranch_execz .LBB0_303
	s_waitcnt lgkmcnt(0)
	s_nop 0
	v_cvt_pk_bf16_f32 v1, v1, v2
	v_add_co_u32_e32 v2, vcc, 0x1000, v80
	s_nop 1
	v_addc_co_u32_e32 v3, vcc, 0, v81, vcc
	global_store_dword v[2:3], v1, off offset:576
.LBB0_303:
	s_or_b64 exec, exec, s[0:1]
	v_mul_f32_e32 v1, v26, v0
	s_waitcnt lgkmcnt(0)
	s_nop 1
	v_mov_b32_dpp v2, v1 quad_perm:[1,0,3,2] row_mask:0xf bank_mask:0xf
	s_and_saveexec_b64 s[0:1], s[4:5]
	s_cbranch_execz .LBB0_305
	s_waitcnt lgkmcnt(0)
	s_nop 0
	v_cvt_pk_bf16_f32 v1, v1, v2
	v_add_co_u32_e32 v2, vcc, 0x1000, v80
	s_nop 1
	v_addc_co_u32_e32 v3, vcc, 0, v81, vcc
	global_store_dword v[2:3], v1, off offset:640
.LBB0_305:
	s_or_b64 exec, exec, s[0:1]
	v_mul_f32_e32 v0, v10, v0
	s_nop 1
	v_mov_b32_dpp v1, v0 quad_perm:[1,0,3,2] row_mask:0xf bank_mask:0xf
	s_and_saveexec_b64 s[0:1], s[4:5]
	s_cbranch_execz .LBB0_307
	s_waitcnt lgkmcnt(0)
	s_nop 0
	v_cvt_pk_bf16_f32 v2, v0, v1
	v_add_co_u32_e32 v0, vcc, 0x1000, v80
	s_nop 1
	v_addc_co_u32_e32 v1, vcc, 0, v81, vcc
	global_store_dword v[0:1], v2, off offset:704
.LBB0_307:
	s_or_b64 exec, exec, s[0:1]
	v_rcp_f32_e32 v0, v71
	s_waitcnt lgkmcnt(0)
	v_mul_f32_e32 v1, v59, v0
	s_nop 1
	v_mov_b32_dpp v2, v1 quad_perm:[1,0,3,2] row_mask:0xf bank_mask:0xf
	s_and_saveexec_b64 s[0:1], s[4:5]
	s_cbranch_execz .LBB0_309
	s_waitcnt lgkmcnt(0)
	s_nop 0
	v_cvt_pk_bf16_f32 v1, v1, v2
	v_add_co_u32_e32 v2, vcc, 0x1000, v80
	s_nop 1
	v_addc_co_u32_e32 v3, vcc, 0, v81, vcc
	global_store_dword v[2:3], v1, off offset:768
.LBB0_309:
	s_or_b64 exec, exec, s[0:1]
	v_mul_f32_e32 v1, v43, v0
	s_waitcnt lgkmcnt(0)
	s_nop 1
	v_mov_b32_dpp v2, v1 quad_perm:[1,0,3,2] row_mask:0xf bank_mask:0xf
	s_and_saveexec_b64 s[0:1], s[4:5]
	s_cbranch_execz .LBB0_311
	s_waitcnt lgkmcnt(0)
	s_nop 0
	v_cvt_pk_bf16_f32 v1, v1, v2
	v_add_co_u32_e32 v2, vcc, 0x1000, v80
	s_nop 1
	v_addc_co_u32_e32 v3, vcc, 0, v81, vcc
	global_store_dword v[2:3], v1, off offset:832
.LBB0_311:
	s_or_b64 exec, exec, s[0:1]
	v_mul_f32_e32 v1, v27, v0
	s_waitcnt lgkmcnt(0)
	s_nop 1
	v_mov_b32_dpp v2, v1 quad_perm:[1,0,3,2] row_mask:0xf bank_mask:0xf
	s_and_saveexec_b64 s[0:1], s[4:5]
	s_cbranch_execz .LBB0_313
	s_waitcnt lgkmcnt(0)
	s_nop 0
	v_cvt_pk_bf16_f32 v1, v1, v2
	v_add_co_u32_e32 v2, vcc, 0x1000, v80
	s_nop 1
	v_addc_co_u32_e32 v3, vcc, 0, v81, vcc
	global_store_dword v[2:3], v1, off offset:896
.LBB0_313:
	s_or_b64 exec, exec, s[0:1]
	v_mul_f32_e32 v0, v11, v0
	s_nop 1
	v_mov_b32_dpp v1, v0 quad_perm:[1,0,3,2] row_mask:0xf bank_mask:0xf
	s_and_saveexec_b64 s[0:1], s[4:5]
	s_cbranch_execz .LBB0_315
	s_waitcnt lgkmcnt(0)
	s_nop 0
	v_cvt_pk_bf16_f32 v2, v0, v1
	v_add_co_u32_e32 v0, vcc, 0x1000, v80
	s_nop 1
	v_addc_co_u32_e32 v1, vcc, 0, v81, vcc
	global_store_dword v[0:1], v2, off offset:960
.LBB0_315:
	s_or_b64 exec, exec, s[0:1]
	v_rcp_f32_e32 v0, v64
	s_waitcnt lgkmcnt(0)
	v_mul_f32_e32 v1, v60, v0
	s_nop 1
	v_mov_b32_dpp v2, v1 quad_perm:[1,0,3,2] row_mask:0xf bank_mask:0xf
	s_and_saveexec_b64 s[0:1], s[4:5]
	s_cbranch_execz .LBB0_317
	s_waitcnt lgkmcnt(0)
	s_nop 0
	v_cvt_pk_bf16_f32 v1, v1, v2
	v_add_co_u32_e32 v2, vcc, 0x1000, v80
	s_nop 1
	v_addc_co_u32_e32 v3, vcc, 0, v81, vcc
	global_store_dword v[2:3], v1, off offset:2048
.LBB0_317:
	s_or_b64 exec, exec, s[0:1]
	v_mul_f32_e32 v1, v44, v0
	s_waitcnt lgkmcnt(0)
	s_nop 1
	v_mov_b32_dpp v2, v1 quad_perm:[1,0,3,2] row_mask:0xf bank_mask:0xf
	s_and_saveexec_b64 s[0:1], s[4:5]
	s_cbranch_execz .LBB0_319
	s_waitcnt lgkmcnt(0)
	s_nop 0
	v_cvt_pk_bf16_f32 v1, v1, v2
	v_add_co_u32_e32 v2, vcc, 0x1000, v80
	s_nop 1
	v_addc_co_u32_e32 v3, vcc, 0, v81, vcc
	global_store_dword v[2:3], v1, off offset:2112
.LBB0_319:
	s_or_b64 exec, exec, s[0:1]
	v_mul_f32_e32 v1, v28, v0
	s_waitcnt lgkmcnt(0)
	s_nop 1
	v_mov_b32_dpp v2, v1 quad_perm:[1,0,3,2] row_mask:0xf bank_mask:0xf
	s_and_saveexec_b64 s[0:1], s[4:5]
	s_cbranch_execz .LBB0_321
	s_waitcnt lgkmcnt(0)
	s_nop 0
	v_cvt_pk_bf16_f32 v1, v1, v2
	v_add_co_u32_e32 v2, vcc, 0x1000, v80
	s_nop 1
	v_addc_co_u32_e32 v3, vcc, 0, v81, vcc
	global_store_dword v[2:3], v1, off offset:2176
.LBB0_321:
	s_or_b64 exec, exec, s[0:1]
	v_mul_f32_e32 v0, v12, v0
	s_nop 1
	v_mov_b32_dpp v1, v0 quad_perm:[1,0,3,2] row_mask:0xf bank_mask:0xf
	s_and_saveexec_b64 s[0:1], s[4:5]
	s_cbranch_execz .LBB0_323
	s_waitcnt lgkmcnt(0)
	s_nop 0
	v_cvt_pk_bf16_f32 v2, v0, v1
	v_add_co_u32_e32 v0, vcc, 0x1000, v80
	s_nop 1
	v_addc_co_u32_e32 v1, vcc, 0, v81, vcc
	global_store_dword v[0:1], v2, off offset:2240
.LBB0_323:
	s_or_b64 exec, exec, s[0:1]
	v_rcp_f32_e32 v0, v65
	s_waitcnt lgkmcnt(0)
	v_mul_f32_e32 v1, v61, v0
	s_nop 1
	v_mov_b32_dpp v2, v1 quad_perm:[1,0,3,2] row_mask:0xf bank_mask:0xf
	s_and_saveexec_b64 s[0:1], s[4:5]
	s_cbranch_execz .LBB0_325
	s_waitcnt lgkmcnt(0)
	s_nop 0
	v_cvt_pk_bf16_f32 v1, v1, v2
	v_add_co_u32_e32 v2, vcc, 0x1000, v80
	s_nop 1
	v_addc_co_u32_e32 v3, vcc, 0, v81, vcc
	global_store_dword v[2:3], v1, off offset:2304
.LBB0_325:
	s_or_b64 exec, exec, s[0:1]
	v_mul_f32_e32 v1, v45, v0
	s_waitcnt lgkmcnt(0)
	s_nop 1
	v_mov_b32_dpp v2, v1 quad_perm:[1,0,3,2] row_mask:0xf bank_mask:0xf
	s_and_saveexec_b64 s[0:1], s[4:5]
	s_cbranch_execz .LBB0_327
	s_waitcnt lgkmcnt(0)
	s_nop 0
	v_cvt_pk_bf16_f32 v1, v1, v2
	v_add_co_u32_e32 v2, vcc, 0x1000, v80
	s_nop 1
	v_addc_co_u32_e32 v3, vcc, 0, v81, vcc
	global_store_dword v[2:3], v1, off offset:2368
.LBB0_327:
	s_or_b64 exec, exec, s[0:1]
	v_mul_f32_e32 v1, v29, v0
	s_waitcnt lgkmcnt(0)
	s_nop 1
	v_mov_b32_dpp v2, v1 quad_perm:[1,0,3,2] row_mask:0xf bank_mask:0xf
	s_and_saveexec_b64 s[0:1], s[4:5]
	s_cbranch_execz .LBB0_329
	s_waitcnt lgkmcnt(0)
	s_nop 0
	v_cvt_pk_bf16_f32 v1, v1, v2
	v_add_co_u32_e32 v2, vcc, 0x1000, v80
	s_nop 1
	v_addc_co_u32_e32 v3, vcc, 0, v81, vcc
	global_store_dword v[2:3], v1, off offset:2432
.LBB0_329:
	s_or_b64 exec, exec, s[0:1]
	v_mul_f32_e32 v0, v13, v0
	s_nop 1
	v_mov_b32_dpp v1, v0 quad_perm:[1,0,3,2] row_mask:0xf bank_mask:0xf
	s_and_saveexec_b64 s[0:1], s[4:5]
	s_cbranch_execz .LBB0_331
	s_waitcnt lgkmcnt(0)
	s_nop 0
	v_cvt_pk_bf16_f32 v2, v0, v1
	v_add_co_u32_e32 v0, vcc, 0x1000, v80
	s_nop 1
	v_addc_co_u32_e32 v1, vcc, 0, v81, vcc
	global_store_dword v[0:1], v2, off offset:2496
.LBB0_331:
	s_or_b64 exec, exec, s[0:1]
	v_rcp_f32_e32 v0, v66
	s_waitcnt lgkmcnt(0)
	v_mul_f32_e32 v1, v62, v0
	s_nop 1
	v_mov_b32_dpp v2, v1 quad_perm:[1,0,3,2] row_mask:0xf bank_mask:0xf
	s_and_saveexec_b64 s[0:1], s[4:5]
	s_cbranch_execz .LBB0_333
	s_waitcnt lgkmcnt(0)
	s_nop 0
	v_cvt_pk_bf16_f32 v1, v1, v2
	v_add_co_u32_e32 v2, vcc, 0x1000, v80
	s_nop 1
	v_addc_co_u32_e32 v3, vcc, 0, v81, vcc
	global_store_dword v[2:3], v1, off offset:2560
.LBB0_333:
	s_or_b64 exec, exec, s[0:1]
	v_mul_f32_e32 v1, v46, v0
	s_waitcnt lgkmcnt(0)
	s_nop 1
	v_mov_b32_dpp v2, v1 quad_perm:[1,0,3,2] row_mask:0xf bank_mask:0xf
	s_and_saveexec_b64 s[0:1], s[4:5]
	s_cbranch_execz .LBB0_335
	s_waitcnt lgkmcnt(0)
	s_nop 0
	v_cvt_pk_bf16_f32 v1, v1, v2
	v_add_co_u32_e32 v2, vcc, 0x1000, v80
	s_nop 1
	v_addc_co_u32_e32 v3, vcc, 0, v81, vcc
	global_store_dword v[2:3], v1, off offset:2624
.LBB0_335:
	s_or_b64 exec, exec, s[0:1]
	v_mul_f32_e32 v1, v30, v0
	s_waitcnt lgkmcnt(0)
	s_nop 1
	v_mov_b32_dpp v2, v1 quad_perm:[1,0,3,2] row_mask:0xf bank_mask:0xf
	s_and_saveexec_b64 s[0:1], s[4:5]
	s_cbranch_execz .LBB0_337
	s_waitcnt lgkmcnt(0)
	s_nop 0
	v_cvt_pk_bf16_f32 v1, v1, v2
	v_add_co_u32_e32 v2, vcc, 0x1000, v80
	s_nop 1
	v_addc_co_u32_e32 v3, vcc, 0, v81, vcc
	global_store_dword v[2:3], v1, off offset:2688
.LBB0_337:
	s_or_b64 exec, exec, s[0:1]
	v_mul_f32_e32 v0, v14, v0
	s_nop 1
	v_mov_b32_dpp v1, v0 quad_perm:[1,0,3,2] row_mask:0xf bank_mask:0xf
	s_and_saveexec_b64 s[0:1], s[4:5]
	s_cbranch_execz .LBB0_339
	s_waitcnt lgkmcnt(0)
	s_nop 0
	v_cvt_pk_bf16_f32 v2, v0, v1
	v_add_co_u32_e32 v0, vcc, 0x1000, v80
	s_nop 1
	v_addc_co_u32_e32 v1, vcc, 0, v81, vcc
	global_store_dword v[0:1], v2, off offset:2752
.LBB0_339:
	s_or_b64 exec, exec, s[0:1]
	v_rcp_f32_e32 v0, v67
	s_waitcnt lgkmcnt(0)
	v_mul_f32_e32 v1, v63, v0
	s_nop 1
	v_mov_b32_dpp v2, v1 quad_perm:[1,0,3,2] row_mask:0xf bank_mask:0xf
	s_and_saveexec_b64 s[0:1], s[4:5]
	s_cbranch_execz .LBB0_341
	s_waitcnt lgkmcnt(0)
	s_nop 0
	v_cvt_pk_bf16_f32 v1, v1, v2
	v_add_co_u32_e32 v2, vcc, 0x1000, v80
	s_nop 1
	v_addc_co_u32_e32 v3, vcc, 0, v81, vcc
	global_store_dword v[2:3], v1, off offset:2816
.LBB0_341:
	s_or_b64 exec, exec, s[0:1]
	v_mul_f32_e32 v1, v47, v0
	s_waitcnt lgkmcnt(0)
	s_nop 1
	v_mov_b32_dpp v2, v1 quad_perm:[1,0,3,2] row_mask:0xf bank_mask:0xf
	s_and_saveexec_b64 s[0:1], s[4:5]
	s_cbranch_execz .LBB0_343
	s_waitcnt lgkmcnt(0)
	s_nop 0
	v_cvt_pk_bf16_f32 v1, v1, v2
	v_add_co_u32_e32 v2, vcc, 0x1000, v80
	s_nop 1
	v_addc_co_u32_e32 v3, vcc, 0, v81, vcc
	global_store_dword v[2:3], v1, off offset:2880
.LBB0_343:
	s_or_b64 exec, exec, s[0:1]
	v_mul_f32_e32 v1, v31, v0
	s_waitcnt lgkmcnt(0)
	s_nop 1
	v_mov_b32_dpp v2, v1 quad_perm:[1,0,3,2] row_mask:0xf bank_mask:0xf
	s_and_saveexec_b64 s[0:1], s[4:5]
	s_cbranch_execz .LBB0_345
	s_waitcnt lgkmcnt(0)
	s_nop 0
	v_cvt_pk_bf16_f32 v1, v1, v2
	v_add_co_u32_e32 v2, vcc, 0x1000, v80
	s_nop 1
	v_addc_co_u32_e32 v3, vcc, 0, v81, vcc
	global_store_dword v[2:3], v1, off offset:2944
.LBB0_345:
	s_or_b64 exec, exec, s[0:1]
	v_mul_f32_e32 v0, v15, v0
	s_nop 1
	v_mov_b32_dpp v1, v0 quad_perm:[1,0,3,2] row_mask:0xf bank_mask:0xf
	s_and_saveexec_b64 s[0:1], s[4:5]
	s_cbranch_execz .LBB0_187
	s_waitcnt lgkmcnt(0)
	s_nop 0
	v_cvt_pk_bf16_f32 v2, v0, v1
	v_add_co_u32_e32 v0, vcc, 0x1000, v80
	s_nop 1
	v_addc_co_u32_e32 v1, vcc, 0, v81, vcc
	global_store_dword v[0:1], v2, off offset:3008
	s_branch .LBB0_187

.LBB0_489:
	s_lshl_b32 s10, s87, 5
	s_add_i32 s13, s10, 0
	s_add_i32 s14, s13, 0x10000
	v_mov_b32_e32 v72, s14
	s_waitcnt lgkmcnt(0)
	s_barrier
	ds_read_b128 v[64:67], v72
	ds_read_b128 v[68:71], v72 offset:16
	s_add_i32 s12, s80, s78
	v_add_u32_e32 v217, 64, v217
	s_cmp_eq_u32 s12, 0
	s_cselect_b64 s[10:11], -1, 0
	s_add_i32 s75, s75, -1
	s_add_i32 s81, s81, 1
	s_waitcnt lgkmcnt(0)
	v_add3_u32 v64, v64, v65, v66
	v_add3_u32 v68, v67, v68, v69
	v_add3_u32 v64, v64, v70, v71
	v_add_u32_e32 v64, v64, v68
	v_cmp_eq_u32_e32 vcc, 8, v64
	s_or_b64 s[10:11], s[10:11], vcc
	s_add_u32 s78, s78, 0xffffc000
	s_addc_u32 s79, s79, -1
	s_sub_i32 s74, s74, 64
	s_and_b64 s[10:11], exec, s[10:11]
	s_or_b64 s[2:3], s[10:11], s[2:3]
	s_andn2_b64 exec, exec, s[2:3]
	s_cbranch_execz .LBB0_506

.LBB0_506:
	s_or_b64 exec, exec, s[2:3]
	s_lshl_b32 s0, s33, 4
	s_and_b32 s0, s0, 0xffffe000
	s_add_i32 s0, s77, s0
	v_and_b32_e32 v65, 64, v204
	s_ashr_i32 s1, s0, 31
	v_xor_b32_e32 v64, 1, v204
	v_add_u32_e32 v65, 64, v65
	s_lshl_b64 s[0:1], s[0:1], 12
	v_cmp_lt_i32_e32 vcc, v64, v65
	s_add_u32 s0, s62, s0
	v_readlane_b32 s2, v246, 36
	v_cndmask_b32_e32 v64, v204, v64, vcc
	s_addc_u32 s1, s63, s1
	s_lshl_b32 s2, s2, 8
	v_lshlrev_b32_e32 v66, 2, v64
	s_and_b32 s2, s2, 0xf00
	s_nop 1
	v_mov_b32_dpp v67, v48 quad_perm:[1,0,3,2] row_mask:0xf bank_mask:0xf
	s_add_u32 s0, s0, s2
	s_addc_u32 s1, s1, 0
	v_mov_b32_e32 v195, v185
	v_lshl_add_u64 v[64:65], s[0:1], 0, v[194:195]
	v_lshl_add_u64 v[64:65], v[64:65], 0, v[190:191]
	v_readlane_b32 s3, v246, 37
	s_and_saveexec_b64 s[0:1], s[8:9]
	s_cbranch_execz .LBB0_508
	s_waitcnt lgkmcnt(0)
	s_nop 0
	v_cvt_pk_bf16_f32 v48, v48, v67
	global_store_dword v[64:65], v48, off
.LBB0_508:
	s_or_b64 exec, exec, s[0:1]
	s_nop 1
	v_mov_b32_dpp v48, v32 quad_perm:[1,0,3,2] row_mask:0xf bank_mask:0xf
	s_and_saveexec_b64 s[0:1], s[8:9]
	v_readlane_b32 s36, v246, 4
	v_readlane_b32 s56, v246, 11
	v_readlane_b32 s37, v246, 5
	v_readlane_b32 s38, v246, 6
	v_readlane_b32 s39, v246, 7
	v_readlane_b32 s57, v246, 12
	v_readlane_b32 s31, v246, 26
	s_movk_i32 s73, 0x2000
	s_mov_b32 s87, 0x41000000
	s_cbranch_execz .LBB0_510
	s_waitcnt lgkmcnt(0)
	s_nop 0
	v_cvt_pk_bf16_f32 v32, v32, v48
	global_store_dword v[64:65], v32, off offset:64
.LBB0_510:
	s_or_b64 exec, exec, s[0:1]
	s_nop 1
	v_mov_b32_dpp v32, v16 quad_perm:[1,0,3,2] row_mask:0xf bank_mask:0xf
	s_and_saveexec_b64 s[0:1], s[8:9]
	s_cbranch_execz .LBB0_512
	s_waitcnt lgkmcnt(0)
	s_nop 0
	v_cvt_pk_bf16_f32 v16, v16, v32
	global_store_dword v[64:65], v16, off offset:128
.LBB0_512:
	s_or_b64 exec, exec, s[0:1]
	s_nop 1
	v_mov_b32_dpp v16, v0 quad_perm:[1,0,3,2] row_mask:0xf bank_mask:0xf
	s_and_saveexec_b64 s[0:1], s[8:9]
	v_readlane_b32 s34, v246, 9
	v_readlane_b32 s58, v246, 13
	v_readlane_b32 s60, v246, 15
	v_readlane_b32 s64, v246, 34
	v_readlane_b32 s35, v246, 10
	v_readlane_b32 s59, v246, 14
	v_readlane_b32 s61, v246, 16
	v_readlane_b32 s65, v246, 35
	s_mov_b32 s88, 0x20000
	s_mov_b32 s89, 0x30000
	s_cbranch_execz .LBB0_514
	s_waitcnt lgkmcnt(0)
	s_nop 0
	v_cvt_pk_bf16_f32 v0, v0, v16
	global_store_dword v[64:65], v0, off offset:192
.LBB0_514:
	s_or_b64 exec, exec, s[0:1]
	s_nop 1
	v_mov_b32_dpp v0, v49 quad_perm:[1,0,3,2] row_mask:0xf bank_mask:0xf
	s_and_saveexec_b64 s[0:1], s[8:9]
	s_cbranch_execz .LBB0_516
	s_waitcnt lgkmcnt(3)
	v_add_co_u32_e32 v48, vcc, 0x1000, v64
	s_waitcnt lgkmcnt(0)
	s_nop 0
	v_cvt_pk_bf16_f32 v0, v49, v0
	s_nop 0
	v_addc_co_u32_e32 v49, vcc, 0, v65, vcc
	global_store_dword v[48:49], v0, off
.LBB0_516:
	s_or_b64 exec, exec, s[0:1]
	s_waitcnt lgkmcnt(0)
	s_nop 1
	v_mov_b32_dpp v0, v33 quad_perm:[1,0,3,2] row_mask:0xf bank_mask:0xf
	s_and_saveexec_b64 s[0:1], s[8:9]
	s_cbranch_execz .LBB0_518
	v_add_co_u32_e32 v32, vcc, 0x1000, v64
	s_waitcnt lgkmcnt(0)
	s_nop 0
	v_cvt_pk_bf16_f32 v0, v33, v0
	s_nop 0
	v_addc_co_u32_e32 v33, vcc, 0, v65, vcc
	global_store_dword v[32:33], v0, off offset:64
.LBB0_518:
	s_or_b64 exec, exec, s[0:1]
	s_waitcnt lgkmcnt(0)
	s_nop 1
	v_mov_b32_dpp v0, v17 quad_perm:[1,0,3,2] row_mask:0xf bank_mask:0xf
	s_and_saveexec_b64 s[0:1], s[8:9]
	s_cbranch_execz .LBB0_520
	v_add_co_u32_e32 v16, vcc, 0x1000, v64
	s_waitcnt lgkmcnt(0)
	s_nop 0
	v_cvt_pk_bf16_f32 v0, v17, v0
	s_nop 0
	v_addc_co_u32_e32 v17, vcc, 0, v65, vcc
	global_store_dword v[16:17], v0, off offset:128
.LBB0_520:
	s_or_b64 exec, exec, s[0:1]
	s_waitcnt lgkmcnt(0)
	s_nop 1
	v_mov_b32_dpp v0, v1 quad_perm:[1,0,3,2] row_mask:0xf bank_mask:0xf
	s_and_saveexec_b64 s[0:1], s[8:9]
	s_cbranch_execz .LBB0_522
	s_waitcnt lgkmcnt(0)
	s_nop 0
	v_cvt_pk_bf16_f32 v16, v1, v0
	v_add_co_u32_e32 v0, vcc, 0x1000, v64
	s_nop 1
	v_addc_co_u32_e32 v1, vcc, 0, v65, vcc
	global_store_dword v[0:1], v16, off offset:192
.LBB0_522:
	s_or_b64 exec, exec, s[0:1]
	s_waitcnt lgkmcnt(0)
	s_nop 1
	v_mov_b32_dpp v0, v50 quad_perm:[1,0,3,2] row_mask:0xf bank_mask:0xf
	s_and_saveexec_b64 s[0:1], s[8:9]
	s_cbranch_execz .LBB0_524
	s_waitcnt lgkmcnt(0)
	s_nop 0
	v_cvt_pk_bf16_f32 v16, v50, v0
	v_add_co_u32_e32 v0, vcc, 0x2000, v64
	s_nop 1
	v_addc_co_u32_e32 v1, vcc, 0, v65, vcc
	global_store_dword v[0:1], v16, off
.LBB0_524:
	s_or_b64 exec, exec, s[0:1]
	s_waitcnt lgkmcnt(0)
	s_nop 1
	v_mov_b32_dpp v0, v34 quad_perm:[1,0,3,2] row_mask:0xf bank_mask:0xf
	s_and_saveexec_b64 s[0:1], s[8:9]
	s_cbranch_execz .LBB0_526
	s_waitcnt lgkmcnt(0)
	s_nop 0
	v_cvt_pk_bf16_f32 v16, v34, v0
	v_add_co_u32_e32 v0, vcc, 0x2000, v64
	s_nop 1
	v_addc_co_u32_e32 v1, vcc, 0, v65, vcc
	global_store_dword v[0:1], v16, off offset:64
.LBB0_526:
	s_or_b64 exec, exec, s[0:1]
	s_waitcnt lgkmcnt(0)
	s_nop 1
	v_mov_b32_dpp v0, v18 quad_perm:[1,0,3,2] row_mask:0xf bank_mask:0xf
	s_and_saveexec_b64 s[0:1], s[8:9]
	s_cbranch_execz .LBB0_528
	s_waitcnt lgkmcnt(0)
	s_nop 0
	v_cvt_pk_bf16_f32 v16, v18, v0
	v_add_co_u32_e32 v0, vcc, 0x2000, v64
	s_nop 1
	v_addc_co_u32_e32 v1, vcc, 0, v65, vcc
	global_store_dword v[0:1], v16, off offset:128
.LBB0_528:
	s_or_b64 exec, exec, s[0:1]
	s_waitcnt lgkmcnt(0)
	s_nop 1
	v_mov_b32_dpp v0, v2 quad_perm:[1,0,3,2] row_mask:0xf bank_mask:0xf
	s_and_saveexec_b64 s[0:1], s[8:9]
	s_cbranch_execz .LBB0_530
	s_waitcnt lgkmcnt(0)
	s_nop 0
	v_cvt_pk_bf16_f32 v2, v2, v0
	v_add_co_u32_e32 v0, vcc, 0x2000, v64
	s_nop 1
	v_addc_co_u32_e32 v1, vcc, 0, v65, vcc
	global_store_dword v[0:1], v2, off offset:192
.LBB0_530:
	s_or_b64 exec, exec, s[0:1]
	s_waitcnt lgkmcnt(0)
	s_nop 1
	v_mov_b32_dpp v0, v51 quad_perm:[1,0,3,2] row_mask:0xf bank_mask:0xf
	s_and_saveexec_b64 s[0:1], s[8:9]
	s_cbranch_execz .LBB0_532
	s_waitcnt lgkmcnt(0)
	s_nop 0
	v_cvt_pk_bf16_f32 v2, v51, v0
	v_add_co_u32_e32 v0, vcc, 0x3000, v64
	s_nop 1
	v_addc_co_u32_e32 v1, vcc, 0, v65, vcc
	global_store_dword v[0:1], v2, off
.LBB0_532:
	s_or_b64 exec, exec, s[0:1]
	s_waitcnt lgkmcnt(0)
	s_nop 1
	v_mov_b32_dpp v0, v35 quad_perm:[1,0,3,2] row_mask:0xf bank_mask:0xf
	s_and_saveexec_b64 s[0:1], s[8:9]
	s_cbranch_execz .LBB0_534
	s_waitcnt lgkmcnt(0)
	s_nop 0
	v_cvt_pk_bf16_f32 v2, v35, v0
	v_add_co_u32_e32 v0, vcc, 0x3000, v64
	s_nop 1
	v_addc_co_u32_e32 v1, vcc, 0, v65, vcc
	global_store_dword v[0:1], v2, off offset:64
.LBB0_534:
	s_or_b64 exec, exec, s[0:1]
	s_waitcnt lgkmcnt(0)
	s_nop 1
	v_mov_b32_dpp v0, v19 quad_perm:[1,0,3,2] row_mask:0xf bank_mask:0xf
	s_and_saveexec_b64 s[0:1], s[8:9]
	s_cbranch_execz .LBB0_536
	s_waitcnt lgkmcnt(0)
	s_nop 0
	v_cvt_pk_bf16_f32 v2, v19, v0
	v_add_co_u32_e32 v0, vcc, 0x3000, v64
	s_nop 1
	v_addc_co_u32_e32 v1, vcc, 0, v65, vcc
	global_store_dword v[0:1], v2, off offset:128
.LBB0_536:
	s_or_b64 exec, exec, s[0:1]
	s_waitcnt lgkmcnt(0)
	s_nop 1
	v_mov_b32_dpp v0, v3 quad_perm:[1,0,3,2] row_mask:0xf bank_mask:0xf
	s_and_saveexec_b64 s[0:1], s[8:9]
	s_cbranch_execz .LBB0_538
	s_waitcnt lgkmcnt(0)
	s_nop 0
	v_cvt_pk_bf16_f32 v2, v3, v0
	v_add_co_u32_e32 v0, vcc, 0x3000, v64
	s_nop 1
	v_addc_co_u32_e32 v1, vcc, 0, v65, vcc
	global_store_dword v[0:1], v2, off offset:192
.LBB0_538:
	s_or_b64 exec, exec, s[0:1]
	s_waitcnt lgkmcnt(0)
	s_nop 1
	v_mov_b32_dpp v0, v52 quad_perm:[1,0,3,2] row_mask:0xf bank_mask:0xf
	s_and_saveexec_b64 s[0:1], s[8:9]
	s_cbranch_execz .LBB0_540
	s_waitcnt lgkmcnt(0)
	s_nop 0
	v_cvt_pk_bf16_f32 v2, v52, v0
	v_add_co_u32_e32 v0, vcc, 0x8000, v64
	s_nop 1
	v_addc_co_u32_e32 v1, vcc, 0, v65, vcc
	global_store_dword v[0:1], v2, off
.LBB0_540:
	s_or_b64 exec, exec, s[0:1]
	s_waitcnt lgkmcnt(0)
	s_nop 1
	v_mov_b32_dpp v0, v36 quad_perm:[1,0,3,2] row_mask:0xf bank_mask:0xf
	s_and_saveexec_b64 s[0:1], s[8:9]
	s_cbranch_execz .LBB0_542
	s_waitcnt lgkmcnt(0)
	s_nop 0
	v_cvt_pk_bf16_f32 v2, v36, v0
	v_add_co_u32_e32 v0, vcc, 0x8000, v64
	s_nop 1
	v_addc_co_u32_e32 v1, vcc, 0, v65, vcc
	global_store_dword v[0:1], v2, off offset:64
.LBB0_542:
	s_or_b64 exec, exec, s[0:1]
	s_waitcnt lgkmcnt(0)
	s_nop 1
	v_mov_b32_dpp v0, v20 quad_perm:[1,0,3,2] row_mask:0xf bank_mask:0xf
	s_and_saveexec_b64 s[0:1], s[8:9]
	s_cbranch_execz .LBB0_544
	s_waitcnt lgkmcnt(0)
	s_nop 0
	v_cvt_pk_bf16_f32 v2, v20, v0
	v_add_co_u32_e32 v0, vcc, 0x8000, v64
	s_nop 1
	v_addc_co_u32_e32 v1, vcc, 0, v65, vcc
	global_store_dword v[0:1], v2, off offset:128
.LBB0_544:
	s_or_b64 exec, exec, s[0:1]
	s_waitcnt lgkmcnt(0)
	s_nop 1
	v_mov_b32_dpp v0, v4 quad_perm:[1,0,3,2] row_mask:0xf bank_mask:0xf
	s_and_saveexec_b64 s[0:1], s[8:9]
	s_cbranch_execz .LBB0_546
	s_waitcnt lgkmcnt(0)
	s_nop 0
	v_cvt_pk_bf16_f32 v2, v4, v0
	v_add_co_u32_e32 v0, vcc, 0x8000, v64
	s_nop 1
	v_addc_co_u32_e32 v1, vcc, 0, v65, vcc
	global_store_dword v[0:1], v2, off offset:192
.LBB0_546:
	s_or_b64 exec, exec, s[0:1]
	s_waitcnt lgkmcnt(0)
	s_nop 1
	v_mov_b32_dpp v0, v53 quad_perm:[1,0,3,2] row_mask:0xf bank_mask:0xf
	s_and_saveexec_b64 s[0:1], s[8:9]
	s_cbranch_execz .LBB0_548
	s_waitcnt lgkmcnt(0)
	s_nop 0
	v_cvt_pk_bf16_f32 v2, v53, v0
	v_add_co_u32_e32 v0, vcc, 0x9000, v64
	s_nop 1
	v_addc_co_u32_e32 v1, vcc, 0, v65, vcc
	global_store_dword v[0:1], v2, off
.LBB0_548:
	s_or_b64 exec, exec, s[0:1]
	s_waitcnt lgkmcnt(0)
	s_nop 1
	v_mov_b32_dpp v0, v37 quad_perm:[1,0,3,2] row_mask:0xf bank_mask:0xf
	s_and_saveexec_b64 s[0:1], s[8:9]
	s_cbranch_execz .LBB0_550
	s_waitcnt lgkmcnt(0)
	s_nop 0
	v_cvt_pk_bf16_f32 v2, v37, v0
	v_add_co_u32_e32 v0, vcc, 0x9000, v64
	s_nop 1
	v_addc_co_u32_e32 v1, vcc, 0, v65, vcc
	global_store_dword v[0:1], v2, off offset:64
.LBB0_550:
	s_or_b64 exec, exec, s[0:1]
	s_waitcnt lgkmcnt(0)
	s_nop 1
	v_mov_b32_dpp v0, v21 quad_perm:[1,0,3,2] row_mask:0xf bank_mask:0xf
	s_and_saveexec_b64 s[0:1], s[8:9]
	s_cbranch_execz .LBB0_552
	s_waitcnt lgkmcnt(0)
	s_nop 0
	v_cvt_pk_bf16_f32 v2, v21, v0
	v_add_co_u32_e32 v0, vcc, 0x9000, v64
	s_nop 1
	v_addc_co_u32_e32 v1, vcc, 0, v65, vcc
	global_store_dword v[0:1], v2, off offset:128
.LBB0_552:
	s_or_b64 exec, exec, s[0:1]
	s_waitcnt lgkmcnt(0)
	s_nop 1
	v_mov_b32_dpp v0, v5 quad_perm:[1,0,3,2] row_mask:0xf bank_mask:0xf
	s_and_saveexec_b64 s[0:1], s[8:9]
	s_cbranch_execz .LBB0_554
	s_waitcnt lgkmcnt(0)
	s_nop 0
	v_cvt_pk_bf16_f32 v2, v5, v0
	v_add_co_u32_e32 v0, vcc, 0x9000, v64
	s_nop 1
	v_addc_co_u32_e32 v1, vcc, 0, v65, vcc
	global_store_dword v[0:1], v2, off offset:192
.LBB0_554:
	s_or_b64 exec, exec, s[0:1]
	s_waitcnt lgkmcnt(0)
	s_nop 1
	v_mov_b32_dpp v0, v54 quad_perm:[1,0,3,2] row_mask:0xf bank_mask:0xf
	s_and_saveexec_b64 s[0:1], s[8:9]
	s_cbranch_execz .LBB0_556
	s_waitcnt lgkmcnt(0)
	s_nop 0
	v_cvt_pk_bf16_f32 v2, v54, v0
	v_add_co_u32_e32 v0, vcc, 0xa000, v64
	s_nop 1
	v_addc_co_u32_e32 v1, vcc, 0, v65, vcc
	global_store_dword v[0:1], v2, off
.LBB0_556:
	s_or_b64 exec, exec, s[0:1]
	s_waitcnt lgkmcnt(0)
	s_nop 1
	v_mov_b32_dpp v0, v38 quad_perm:[1,0,3,2] row_mask:0xf bank_mask:0xf
	s_and_saveexec_b64 s[0:1], s[8:9]
	s_cbranch_execz .LBB0_558
	s_waitcnt lgkmcnt(0)
	s_nop 0
	v_cvt_pk_bf16_f32 v2, v38, v0
	v_add_co_u32_e32 v0, vcc, 0xa000, v64
	s_nop 1
	v_addc_co_u32_e32 v1, vcc, 0, v65, vcc
	global_store_dword v[0:1], v2, off offset:64
.LBB0_558:
	s_or_b64 exec, exec, s[0:1]
	s_waitcnt lgkmcnt(0)
	s_nop 1
	v_mov_b32_dpp v0, v22 quad_perm:[1,0,3,2] row_mask:0xf bank_mask:0xf
	s_and_saveexec_b64 s[0:1], s[8:9]
	s_cbranch_execz .LBB0_560
	s_waitcnt lgkmcnt(0)
	s_nop 0
	v_cvt_pk_bf16_f32 v2, v22, v0
	v_add_co_u32_e32 v0, vcc, 0xa000, v64
	s_nop 1
	v_addc_co_u32_e32 v1, vcc, 0, v65, vcc
	global_store_dword v[0:1], v2, off offset:128
.LBB0_560:
	s_or_b64 exec, exec, s[0:1]
	s_waitcnt lgkmcnt(0)
	s_nop 1
	v_mov_b32_dpp v0, v6 quad_perm:[1,0,3,2] row_mask:0xf bank_mask:0xf
	s_and_saveexec_b64 s[0:1], s[8:9]
	s_cbranch_execz .LBB0_562
	s_waitcnt lgkmcnt(0)
	s_nop 0
	v_cvt_pk_bf16_f32 v2, v6, v0
	v_add_co_u32_e32 v0, vcc, 0xa000, v64
	s_nop 1
	v_addc_co_u32_e32 v1, vcc, 0, v65, vcc
	global_store_dword v[0:1], v2, off offset:192
.LBB0_562:
	s_or_b64 exec, exec, s[0:1]
	s_waitcnt lgkmcnt(0)
	s_nop 1
	v_mov_b32_dpp v0, v55 quad_perm:[1,0,3,2] row_mask:0xf bank_mask:0xf
	s_and_saveexec_b64 s[0:1], s[8:9]
	s_cbranch_execz .LBB0_564
	s_waitcnt lgkmcnt(0)
	s_nop 0
	v_cvt_pk_bf16_f32 v2, v55, v0
	v_add_co_u32_e32 v0, vcc, 0xb000, v64
	s_nop 1
	v_addc_co_u32_e32 v1, vcc, 0, v65, vcc
	global_store_dword v[0:1], v2, off
.LBB0_564:
	s_or_b64 exec, exec, s[0:1]
	s_waitcnt lgkmcnt(0)
	s_nop 1
	v_mov_b32_dpp v0, v39 quad_perm:[1,0,3,2] row_mask:0xf bank_mask:0xf
	s_and_saveexec_b64 s[0:1], s[8:9]
	s_cbranch_execz .LBB0_566
	s_waitcnt lgkmcnt(0)
	s_nop 0
	v_cvt_pk_bf16_f32 v2, v39, v0
	v_add_co_u32_e32 v0, vcc, 0xb000, v64
	s_nop 1
	v_addc_co_u32_e32 v1, vcc, 0, v65, vcc
	global_store_dword v[0:1], v2, off offset:64
.LBB0_566:
	s_or_b64 exec, exec, s[0:1]
	s_waitcnt lgkmcnt(0)
	s_nop 1
	v_mov_b32_dpp v0, v23 quad_perm:[1,0,3,2] row_mask:0xf bank_mask:0xf
	s_and_saveexec_b64 s[0:1], s[8:9]
	s_cbranch_execz .LBB0_568
	s_waitcnt lgkmcnt(0)
	s_nop 0
	v_cvt_pk_bf16_f32 v2, v23, v0
	v_add_co_u32_e32 v0, vcc, 0xb000, v64
	s_nop 1
	v_addc_co_u32_e32 v1, vcc, 0, v65, vcc
	global_store_dword v[0:1], v2, off offset:128
.LBB0_568:
	s_or_b64 exec, exec, s[0:1]
	s_waitcnt lgkmcnt(0)
	s_nop 1
	v_mov_b32_dpp v0, v7 quad_perm:[1,0,3,2] row_mask:0xf bank_mask:0xf
	s_and_saveexec_b64 s[0:1], s[8:9]
	s_cbranch_execz .LBB0_570
	s_waitcnt lgkmcnt(0)
	s_nop 0
	v_cvt_pk_bf16_f32 v2, v7, v0
	v_add_co_u32_e32 v0, vcc, 0xb000, v64
	s_nop 1
	v_addc_co_u32_e32 v1, vcc, 0, v65, vcc
	global_store_dword v[0:1], v2, off offset:192
.LBB0_570:
	s_or_b64 exec, exec, s[0:1]
	s_waitcnt lgkmcnt(0)
	s_nop 1
	v_mov_b32_dpp v0, v56 quad_perm:[1,0,3,2] row_mask:0xf bank_mask:0xf
	s_and_saveexec_b64 s[0:1], s[8:9]
	s_cbranch_execz .LBB0_572
	s_waitcnt lgkmcnt(0)
	s_nop 0
	v_cvt_pk_bf16_f32 v2, v56, v0
	v_add_co_u32_e32 v0, vcc, 0x10000, v64
	s_nop 1
	v_addc_co_u32_e32 v1, vcc, 0, v65, vcc
	global_store_dword v[0:1], v2, off
.LBB0_572:
	s_or_b64 exec, exec, s[0:1]
	s_waitcnt lgkmcnt(0)
	s_nop 1
	v_mov_b32_dpp v0, v40 quad_perm:[1,0,3,2] row_mask:0xf bank_mask:0xf
	s_and_saveexec_b64 s[0:1], s[8:9]
	s_cbranch_execz .LBB0_574
	s_waitcnt lgkmcnt(0)
	s_nop 0
	v_cvt_pk_bf16_f32 v2, v40, v0
	v_add_co_u32_e32 v0, vcc, 0x10000, v64
	s_nop 1
	v_addc_co_u32_e32 v1, vcc, 0, v65, vcc
	global_store_dword v[0:1], v2, off offset:64
.LBB0_574:
	s_or_b64 exec, exec, s[0:1]
	s_waitcnt lgkmcnt(0)
	s_nop 1
	v_mov_b32_dpp v0, v24 quad_perm:[1,0,3,2] row_mask:0xf bank_mask:0xf
	s_and_saveexec_b64 s[0:1], s[8:9]
	s_cbranch_execz .LBB0_576
	s_waitcnt lgkmcnt(0)
	s_nop 0
	v_cvt_pk_bf16_f32 v2, v24, v0
	v_add_co_u32_e32 v0, vcc, 0x10000, v64
	s_nop 1
	v_addc_co_u32_e32 v1, vcc, 0, v65, vcc
	global_store_dword v[0:1], v2, off offset:128
.LBB0_576:
	s_or_b64 exec, exec, s[0:1]
	s_waitcnt lgkmcnt(0)
	s_nop 1
	v_mov_b32_dpp v0, v8 quad_perm:[1,0,3,2] row_mask:0xf bank_mask:0xf
	s_and_saveexec_b64 s[0:1], s[8:9]
	s_cbranch_execz .LBB0_578
	s_waitcnt lgkmcnt(0)
	s_nop 0
	v_cvt_pk_bf16_f32 v2, v8, v0
	v_add_co_u32_e32 v0, vcc, 0x10000, v64
	s_nop 1
	v_addc_co_u32_e32 v1, vcc, 0, v65, vcc
	global_store_dword v[0:1], v2, off offset:192
.LBB0_578:
	s_or_b64 exec, exec, s[0:1]
	s_waitcnt lgkmcnt(0)
	s_nop 1
	v_mov_b32_dpp v0, v57 quad_perm:[1,0,3,2] row_mask:0xf bank_mask:0xf
	s_and_saveexec_b64 s[0:1], s[8:9]
	s_cbranch_execz .LBB0_580
	s_waitcnt lgkmcnt(0)
	s_nop 0
	v_cvt_pk_bf16_f32 v2, v57, v0
	v_add_co_u32_e32 v0, vcc, 0x11000, v64
	s_nop 1
	v_addc_co_u32_e32 v1, vcc, 0, v65, vcc
	global_store_dword v[0:1], v2, off
.LBB0_580:
	s_or_b64 exec, exec, s[0:1]
	s_waitcnt lgkmcnt(0)
	s_nop 1
	v_mov_b32_dpp v0, v41 quad_perm:[1,0,3,2] row_mask:0xf bank_mask:0xf
	s_and_saveexec_b64 s[0:1], s[8:9]
	s_cbranch_execz .LBB0_582
	s_waitcnt lgkmcnt(0)
	s_nop 0
	v_cvt_pk_bf16_f32 v2, v41, v0
	v_add_co_u32_e32 v0, vcc, 0x11000, v64
	s_nop 1
	v_addc_co_u32_e32 v1, vcc, 0, v65, vcc
	global_store_dword v[0:1], v2, off offset:64
.LBB0_582:
	s_or_b64 exec, exec, s[0:1]
	s_waitcnt lgkmcnt(0)
	s_nop 1
	v_mov_b32_dpp v0, v25 quad_perm:[1,0,3,2] row_mask:0xf bank_mask:0xf
	s_and_saveexec_b64 s[0:1], s[8:9]
	s_cbranch_execz .LBB0_584
	s_waitcnt lgkmcnt(0)
	s_nop 0
	v_cvt_pk_bf16_f32 v2, v25, v0
	v_add_co_u32_e32 v0, vcc, 0x11000, v64
	s_nop 1
	v_addc_co_u32_e32 v1, vcc, 0, v65, vcc
	global_store_dword v[0:1], v2, off offset:128
.LBB0_584:
	s_or_b64 exec, exec, s[0:1]
	s_waitcnt lgkmcnt(0)
	s_nop 1
	v_mov_b32_dpp v0, v9 quad_perm:[1,0,3,2] row_mask:0xf bank_mask:0xf
	s_and_saveexec_b64 s[0:1], s[8:9]
	s_cbranch_execz .LBB0_586
	s_waitcnt lgkmcnt(0)
	s_nop 0
	v_cvt_pk_bf16_f32 v2, v9, v0
	v_add_co_u32_e32 v0, vcc, 0x11000, v64
	s_nop 1
	v_addc_co_u32_e32 v1, vcc, 0, v65, vcc
	global_store_dword v[0:1], v2, off offset:192
.LBB0_586:
	s_or_b64 exec, exec, s[0:1]
	s_waitcnt lgkmcnt(0)
	s_nop 1
	v_mov_b32_dpp v0, v58 quad_perm:[1,0,3,2] row_mask:0xf bank_mask:0xf
	s_and_saveexec_b64 s[0:1], s[8:9]
	s_cbranch_execz .LBB0_588
	s_waitcnt lgkmcnt(0)
	s_nop 0
	v_cvt_pk_bf16_f32 v2, v58, v0
	v_add_co_u32_e32 v0, vcc, 0x12000, v64
	s_nop 1
	v_addc_co_u32_e32 v1, vcc, 0, v65, vcc
	global_store_dword v[0:1], v2, off
.LBB0_588:
	s_or_b64 exec, exec, s[0:1]
	s_waitcnt lgkmcnt(0)
	s_nop 1
	v_mov_b32_dpp v0, v42 quad_perm:[1,0,3,2] row_mask:0xf bank_mask:0xf
	s_and_saveexec_b64 s[0:1], s[8:9]
	s_cbranch_execz .LBB0_590
	s_waitcnt lgkmcnt(0)
	s_nop 0
	v_cvt_pk_bf16_f32 v2, v42, v0
	v_add_co_u32_e32 v0, vcc, 0x12000, v64
	s_nop 1
	v_addc_co_u32_e32 v1, vcc, 0, v65, vcc
	global_store_dword v[0:1], v2, off offset:64
.LBB0_590:
	s_or_b64 exec, exec, s[0:1]
	s_waitcnt lgkmcnt(0)
	s_nop 1
	v_mov_b32_dpp v0, v26 quad_perm:[1,0,3,2] row_mask:0xf bank_mask:0xf
	s_and_saveexec_b64 s[0:1], s[8:9]
	s_cbranch_execz .LBB0_592
	s_waitcnt lgkmcnt(0)
	s_nop 0
	v_cvt_pk_bf16_f32 v2, v26, v0
	v_add_co_u32_e32 v0, vcc, 0x12000, v64
	s_nop 1
	v_addc_co_u32_e32 v1, vcc, 0, v65, vcc
	global_store_dword v[0:1], v2, off offset:128
.LBB0_592:
	s_or_b64 exec, exec, s[0:1]
	s_waitcnt lgkmcnt(0)
	s_nop 1
	v_mov_b32_dpp v0, v10 quad_perm:[1,0,3,2] row_mask:0xf bank_mask:0xf
	s_and_saveexec_b64 s[0:1], s[8:9]
	s_cbranch_execz .LBB0_594
	s_waitcnt lgkmcnt(0)
	s_nop 0
	v_cvt_pk_bf16_f32 v2, v10, v0
	v_add_co_u32_e32 v0, vcc, 0x12000, v64
	s_nop 1
	v_addc_co_u32_e32 v1, vcc, 0, v65, vcc
	global_store_dword v[0:1], v2, off offset:192
.LBB0_594:
	s_or_b64 exec, exec, s[0:1]
	s_waitcnt lgkmcnt(0)
	s_nop 1
	v_mov_b32_dpp v0, v59 quad_perm:[1,0,3,2] row_mask:0xf bank_mask:0xf
	s_and_saveexec_b64 s[0:1], s[8:9]
	s_cbranch_execz .LBB0_596
	s_waitcnt lgkmcnt(0)
	s_nop 0
	v_cvt_pk_bf16_f32 v2, v59, v0
	v_add_co_u32_e32 v0, vcc, 0x13000, v64
	s_nop 1
	v_addc_co_u32_e32 v1, vcc, 0, v65, vcc
	global_store_dword v[0:1], v2, off
.LBB0_596:
	s_or_b64 exec, exec, s[0:1]
	s_waitcnt lgkmcnt(0)
	s_nop 1
	v_mov_b32_dpp v0, v43 quad_perm:[1,0,3,2] row_mask:0xf bank_mask:0xf
	s_and_saveexec_b64 s[0:1], s[8:9]
	s_cbranch_execz .LBB0_598
	s_waitcnt lgkmcnt(0)
	s_nop 0
	v_cvt_pk_bf16_f32 v2, v43, v0
	v_add_co_u32_e32 v0, vcc, 0x13000, v64
	s_nop 1
	v_addc_co_u32_e32 v1, vcc, 0, v65, vcc
	global_store_dword v[0:1], v2, off offset:64
.LBB0_598:
	s_or_b64 exec, exec, s[0:1]
	s_waitcnt lgkmcnt(0)
	s_nop 1
	v_mov_b32_dpp v0, v27 quad_perm:[1,0,3,2] row_mask:0xf bank_mask:0xf
	s_and_saveexec_b64 s[0:1], s[8:9]
	s_cbranch_execz .LBB0_600
	s_waitcnt lgkmcnt(0)
	s_nop 0
	v_cvt_pk_bf16_f32 v2, v27, v0
	v_add_co_u32_e32 v0, vcc, 0x13000, v64
	s_nop 1
	v_addc_co_u32_e32 v1, vcc, 0, v65, vcc
	global_store_dword v[0:1], v2, off offset:128
.LBB0_600:
	s_or_b64 exec, exec, s[0:1]
	s_waitcnt lgkmcnt(0)
	s_nop 1
	v_mov_b32_dpp v0, v11 quad_perm:[1,0,3,2] row_mask:0xf bank_mask:0xf
	s_and_saveexec_b64 s[0:1], s[8:9]
	s_cbranch_execz .LBB0_602
	s_waitcnt lgkmcnt(0)
	s_nop 0
	v_cvt_pk_bf16_f32 v2, v11, v0
	v_add_co_u32_e32 v0, vcc, 0x13000, v64
	s_nop 1
	v_addc_co_u32_e32 v1, vcc, 0, v65, vcc
	global_store_dword v[0:1], v2, off offset:192
.LBB0_602:
	s_or_b64 exec, exec, s[0:1]
	s_waitcnt lgkmcnt(0)
	s_nop 1
	v_mov_b32_dpp v0, v60 quad_perm:[1,0,3,2] row_mask:0xf bank_mask:0xf
	s_and_saveexec_b64 s[0:1], s[8:9]
	s_cbranch_execz .LBB0_604
	s_waitcnt lgkmcnt(0)
	s_nop 0
	v_cvt_pk_bf16_f32 v2, v60, v0
	v_add_co_u32_e32 v0, vcc, 0x18000, v64
	s_nop 1
	v_addc_co_u32_e32 v1, vcc, 0, v65, vcc
	global_store_dword v[0:1], v2, off
.LBB0_604:
	s_or_b64 exec, exec, s[0:1]
	s_waitcnt lgkmcnt(0)
	s_nop 1
	v_mov_b32_dpp v0, v44 quad_perm:[1,0,3,2] row_mask:0xf bank_mask:0xf
	s_and_saveexec_b64 s[0:1], s[8:9]
	s_cbranch_execz .LBB0_606
	s_waitcnt lgkmcnt(0)
	s_nop 0
	v_cvt_pk_bf16_f32 v2, v44, v0
	v_add_co_u32_e32 v0, vcc, 0x18000, v64
	s_nop 1
	v_addc_co_u32_e32 v1, vcc, 0, v65, vcc
	global_store_dword v[0:1], v2, off offset:64
.LBB0_606:
	s_or_b64 exec, exec, s[0:1]
	s_waitcnt lgkmcnt(0)
	s_nop 1
	v_mov_b32_dpp v0, v28 quad_perm:[1,0,3,2] row_mask:0xf bank_mask:0xf
	s_and_saveexec_b64 s[0:1], s[8:9]
	s_cbranch_execz .LBB0_608
	s_waitcnt lgkmcnt(0)
	s_nop 0
	v_cvt_pk_bf16_f32 v2, v28, v0
	v_add_co_u32_e32 v0, vcc, 0x18000, v64
	s_nop 1
	v_addc_co_u32_e32 v1, vcc, 0, v65, vcc
	global_store_dword v[0:1], v2, off offset:128
.LBB0_608:
	s_or_b64 exec, exec, s[0:1]
	s_waitcnt lgkmcnt(0)
	s_nop 1
	v_mov_b32_dpp v0, v12 quad_perm:[1,0,3,2] row_mask:0xf bank_mask:0xf
	s_and_saveexec_b64 s[0:1], s[8:9]
	s_cbranch_execz .LBB0_610
	s_waitcnt lgkmcnt(0)
	s_nop 0
	v_cvt_pk_bf16_f32 v2, v12, v0
	v_add_co_u32_e32 v0, vcc, 0x18000, v64
	s_nop 1
	v_addc_co_u32_e32 v1, vcc, 0, v65, vcc
	global_store_dword v[0:1], v2, off offset:192
.LBB0_610:
	s_or_b64 exec, exec, s[0:1]
	s_waitcnt lgkmcnt(0)
	s_nop 1
	v_mov_b32_dpp v0, v61 quad_perm:[1,0,3,2] row_mask:0xf bank_mask:0xf
	s_and_saveexec_b64 s[0:1], s[8:9]
	s_cbranch_execz .LBB0_612
	s_waitcnt lgkmcnt(0)
	s_nop 0
	v_cvt_pk_bf16_f32 v2, v61, v0
	v_add_co_u32_e32 v0, vcc, 0x19000, v64
	s_nop 1
	v_addc_co_u32_e32 v1, vcc, 0, v65, vcc
	global_store_dword v[0:1], v2, off
.LBB0_612:
	s_or_b64 exec, exec, s[0:1]
	s_waitcnt lgkmcnt(0)
	s_nop 1
	v_mov_b32_dpp v0, v45 quad_perm:[1,0,3,2] row_mask:0xf bank_mask:0xf
	s_and_saveexec_b64 s[0:1], s[8:9]
	s_cbranch_execz .LBB0_614
	s_waitcnt lgkmcnt(0)
	s_nop 0
	v_cvt_pk_bf16_f32 v2, v45, v0
	v_add_co_u32_e32 v0, vcc, 0x19000, v64
	s_nop 1
	v_addc_co_u32_e32 v1, vcc, 0, v65, vcc
	global_store_dword v[0:1], v2, off offset:64
.LBB0_614:
	s_or_b64 exec, exec, s[0:1]
	s_waitcnt lgkmcnt(0)
	s_nop 1
	v_mov_b32_dpp v0, v29 quad_perm:[1,0,3,2] row_mask:0xf bank_mask:0xf
	s_and_saveexec_b64 s[0:1], s[8:9]
	s_cbranch_execz .LBB0_616
	s_waitcnt lgkmcnt(0)
	s_nop 0
	v_cvt_pk_bf16_f32 v2, v29, v0
	v_add_co_u32_e32 v0, vcc, 0x19000, v64
	s_nop 1
	v_addc_co_u32_e32 v1, vcc, 0, v65, vcc
	global_store_dword v[0:1], v2, off offset:128
.LBB0_616:
	s_or_b64 exec, exec, s[0:1]
	s_waitcnt lgkmcnt(0)
	s_nop 1
	v_mov_b32_dpp v0, v13 quad_perm:[1,0,3,2] row_mask:0xf bank_mask:0xf
	s_and_saveexec_b64 s[0:1], s[8:9]
	s_cbranch_execz .LBB0_618
	s_waitcnt lgkmcnt(0)
	s_nop 0
	v_cvt_pk_bf16_f32 v2, v13, v0
	v_add_co_u32_e32 v0, vcc, 0x19000, v64
	s_nop 1
	v_addc_co_u32_e32 v1, vcc, 0, v65, vcc
	global_store_dword v[0:1], v2, off offset:192
.LBB0_618:
	s_or_b64 exec, exec, s[0:1]
	s_waitcnt lgkmcnt(0)
	s_nop 1
	v_mov_b32_dpp v0, v62 quad_perm:[1,0,3,2] row_mask:0xf bank_mask:0xf
	s_and_saveexec_b64 s[0:1], s[8:9]
	s_cbranch_execz .LBB0_620
	s_waitcnt lgkmcnt(0)
	s_nop 0
	v_cvt_pk_bf16_f32 v2, v62, v0
	v_add_co_u32_e32 v0, vcc, 0x1a000, v64
	s_nop 1
	v_addc_co_u32_e32 v1, vcc, 0, v65, vcc
	global_store_dword v[0:1], v2, off
.LBB0_620:
	s_or_b64 exec, exec, s[0:1]
	s_waitcnt lgkmcnt(0)
	s_nop 1
	v_mov_b32_dpp v0, v46 quad_perm:[1,0,3,2] row_mask:0xf bank_mask:0xf
	s_and_saveexec_b64 s[0:1], s[8:9]
	s_cbranch_execz .LBB0_622
	s_waitcnt lgkmcnt(0)
	s_nop 0
	v_cvt_pk_bf16_f32 v2, v46, v0
	v_add_co_u32_e32 v0, vcc, 0x1a000, v64
	s_nop 1
	v_addc_co_u32_e32 v1, vcc, 0, v65, vcc
	global_store_dword v[0:1], v2, off offset:64
.LBB0_622:
	s_or_b64 exec, exec, s[0:1]
	s_waitcnt lgkmcnt(0)
	s_nop 1
	v_mov_b32_dpp v0, v30 quad_perm:[1,0,3,2] row_mask:0xf bank_mask:0xf
	s_and_saveexec_b64 s[0:1], s[8:9]
	s_cbranch_execz .LBB0_624
	s_waitcnt lgkmcnt(0)
	s_nop 0
	v_cvt_pk_bf16_f32 v2, v30, v0
	v_add_co_u32_e32 v0, vcc, 0x1a000, v64
	s_nop 1
	v_addc_co_u32_e32 v1, vcc, 0, v65, vcc
	global_store_dword v[0:1], v2, off offset:128
.LBB0_624:
	s_or_b64 exec, exec, s[0:1]
	s_waitcnt lgkmcnt(0)
	s_nop 1
	v_mov_b32_dpp v0, v14 quad_perm:[1,0,3,2] row_mask:0xf bank_mask:0xf
	s_and_saveexec_b64 s[0:1], s[8:9]
	s_cbranch_execz .LBB0_626
	s_waitcnt lgkmcnt(0)
	s_nop 0
	v_cvt_pk_bf16_f32 v2, v14, v0
	v_add_co_u32_e32 v0, vcc, 0x1a000, v64
	s_nop 1
	v_addc_co_u32_e32 v1, vcc, 0, v65, vcc
	global_store_dword v[0:1], v2, off offset:192
.LBB0_626:
	s_or_b64 exec, exec, s[0:1]
	s_waitcnt lgkmcnt(0)
	s_nop 1
	v_mov_b32_dpp v0, v63 quad_perm:[1,0,3,2] row_mask:0xf bank_mask:0xf
	s_and_saveexec_b64 s[0:1], s[8:9]
	s_cbranch_execz .LBB0_628
	s_waitcnt lgkmcnt(0)
	s_nop 0
	v_cvt_pk_bf16_f32 v2, v63, v0
	v_add_co_u32_e32 v0, vcc, 0x1b000, v64
	s_nop 1
	v_addc_co_u32_e32 v1, vcc, 0, v65, vcc
	global_store_dword v[0:1], v2, off
.LBB0_628:
	s_or_b64 exec, exec, s[0:1]
	s_waitcnt lgkmcnt(0)
	s_nop 1
	v_mov_b32_dpp v0, v47 quad_perm:[1,0,3,2] row_mask:0xf bank_mask:0xf
	s_and_saveexec_b64 s[0:1], s[8:9]
	s_cbranch_execz .LBB0_630
	s_waitcnt lgkmcnt(0)
	s_nop 0
	v_cvt_pk_bf16_f32 v2, v47, v0
	v_add_co_u32_e32 v0, vcc, 0x1b000, v64
	s_nop 1
	v_addc_co_u32_e32 v1, vcc, 0, v65, vcc
	global_store_dword v[0:1], v2, off offset:64
.LBB0_630:
	s_or_b64 exec, exec, s[0:1]
	s_waitcnt lgkmcnt(0)
	s_nop 1
	v_mov_b32_dpp v0, v31 quad_perm:[1,0,3,2] row_mask:0xf bank_mask:0xf
	s_and_saveexec_b64 s[0:1], s[8:9]
	s_cbranch_execz .LBB0_632
	s_waitcnt lgkmcnt(0)
	s_nop 0
	v_cvt_pk_bf16_f32 v2, v31, v0
	v_add_co_u32_e32 v0, vcc, 0x1b000, v64
	s_nop 1
	v_addc_co_u32_e32 v1, vcc, 0, v65, vcc
	global_store_dword v[0:1], v2, off offset:128
.LBB0_632:
	s_or_b64 exec, exec, s[0:1]
	s_waitcnt lgkmcnt(0)
	s_nop 1
	v_mov_b32_dpp v0, v15 quad_perm:[1,0,3,2] row_mask:0xf bank_mask:0xf
	s_and_saveexec_b64 s[0:1], s[8:9]
	s_cbranch_execz .LBB0_487
	s_waitcnt lgkmcnt(0)
	s_nop 0
	v_cvt_pk_bf16_f32 v2, v15, v0
	v_add_co_u32_e32 v0, vcc, 0x1b000, v64
	s_nop 1
	v_addc_co_u32_e32 v1, vcc, 0, v65, vcc
	global_store_dword v[0:1], v2, off offset:192
	s_branch .LBB0_487
